# attn1 (forgetting attention): P-fragment permlane swaps removed the same way (natural key order for the staged V tile)
# speedup vs baseline: 1.0010x; 1.0010x over previous
.LBB0_1159:
	s_waitcnt lgkmcnt(0)
	v_bfe_u32 v2, v181, 4, 2
	v_and_b32_e32 v4, 15, v181
	v_or_b32_e32 v3, s85, v2
	v_bitop3_b32 v5, v2, v181, 15 bitop3:0x78
	v_bitop3_b32 v2, v2, v4, 4 bitop3:0x36
	v_lshlrev_b32_e32 v3, 8, v3
	v_lshlrev_b32_e32 v2, 4, v2
	s_movk_i32 s52, 0x400
	v_lshl_or_b32 v183, v5, 4, v3
	v_or3_b32 v184, v2, v3, s52
	v_bfe_u32 v2, v181, 2, 3
	v_lshrrev_b32_e32 v3, 2, v181
	v_and_b32_e32 v182, 63, v181
	v_bitop3_b32 v2, v2, 51, s85 bitop3:0xc8
	v_and_b32_e32 v3, 4, v3
	v_lshlrev_b32_e32 v1, 3, v182
	v_lshl_or_b32 v2, s82, 1, v2
	v_or_b32_e32 v2, v3, v2
	v_and_b32_e32 v34, 24, v1
	v_lshlrev_b32_e32 v2, 7, v2
	v_and_b32_e32 v3, 32, v181
	v_or3_b32 v2, v2, v3, v34
	v_lshlrev_b32_e32 v187, 1, v2
	v_or_b32_e32 v186, 0x80, v187
	v_lshlrev_b32_e32 v185, 2, v182
	s_andn2_b64 vcc, exec, s[8:9]
	s_or_b32 s52, s84, 3
	s_cbranch_vccnz .LBB0_1161
	s_mov_b32 s53, s13
	s_lshl_b64 s[8:9], s[52:53], 14
	s_add_u32 s62, s54, s8
	s_addc_u32 s63, s55, s9
	s_lshl_b64 s[6:7], s[12:13], 14
	s_add_u32 s66, s54, s6
	s_addc_u32 s67, s55, s7
	s_add_u32 s8, s56, s8
	s_mov_b32 s64, m0
	s_mov_b32 m0, s90
	s_nop 0
	global_load_lds_dwordx4 v183, s[62:63]
	s_mov_b32 m0, s64
	s_addc_u32 s9, s57, s9
	s_mov_b32 s64, m0
	s_mov_b32 m0, s2
	s_nop 0
	global_load_lds_dwordx4 v184, s[62:63]
	s_mov_b32 m0, s64
	s_lshl_b64 s[62:63], s[52:53], 8
	s_add_u32 s62, s58, s62
	s_addc_u32 s63, s59, s63
	s_cmp_lg_u32 0, -1
	s_cselect_b32 s53, 0, 0
	s_add_i32 s64, s53, 0x18800
	s_mov_b32 s68, m0
	s_mov_b32 m0, s64
	s_nop 0
	global_load_lds_dword v185, s[62:63]
	s_mov_b32 m0, s68
	s_mov_b32 s62, m0
	s_mov_b32 m0, s83
	s_nop 0
	global_load_lds_dwordx4 v187, s[8:9]
	s_mov_b32 m0, s62
	s_mov_b32 s65, 0
	s_mov_b32 s62, m0
	s_mov_b32 m0, s3
	s_nop 0
	global_load_lds_dwordx4 v186, s[8:9]
	s_mov_b32 m0, s62
	s_mov_b32 s8, m0
	s_mov_b32 m0, s36
	s_nop 0
	global_load_lds_dwordx4 v183, s[66:67]
	s_mov_b32 m0, s8
	s_mov_b32 s68, 0x8000
	s_mov_b32 s8, m0
	s_mov_b32 m0, s37
	s_nop 0
	global_load_lds_dwordx4 v184, s[66:67]
	s_mov_b32 m0, s8
	s_lshl_b64 s[8:9], s[12:13], 8
	s_add_u32 s8, s58, s8
	s_addc_u32 s9, s59, s9
	s_add_i32 s53, s53, 0x18900
	s_mov_b32 s12, m0
	s_mov_b32 m0, s53
	s_nop 0
	global_load_lds_dword v185, s[8:9]
	s_mov_b32 m0, s12
	s_movk_i32 s53, 0x4000

.LBB0_1169:
	s_mov_b32 s61, s53
	s_mov_b32 s53, s65
	s_ashr_i32 s65, s64, 31
	s_lshl_b64 s[66:67], s[64:65], 14
	s_add_u32 s8, s54, s66
	s_addc_u32 s9, s55, s67
	s_add_i32 s70, s53, s90
	s_mov_b32 s71, m0
	s_mov_b32 m0, s70
	s_nop 0
	global_load_lds_dwordx4 v183, s[8:9]
	s_mov_b32 m0, s71
	s_addk_i32 s70, 0x400
	s_mov_b32 s71, m0
	s_mov_b32 m0, s70
	s_nop 0
	global_load_lds_dwordx4 v184, s[8:9]
	s_mov_b32 m0, s71
	s_lshl_b64 s[8:9], s[64:65], 8
	s_add_u32 s8, s58, s8
	s_addc_u32 s9, s59, s9
	s_ashr_i32 s65, s53, 6
	s_cmp_lg_u32 0, -1
	s_cselect_b32 s70, 0, 0
	s_add_i32 s65, s70, s65
	s_add_i32 s65, s65, 0x18800
	s_mov_b32 s70, m0
	s_mov_b32 m0, s65
	s_nop 0
	global_load_lds_dword v185, s[8:9]
	s_mov_b32 m0, s70
	s_add_i32 s8, s64, 1
	s_ashr_i32 s9, s8, 31
	s_lshl_b64 s[8:9], s[8:9], 14
	s_add_u32 s8, s56, s8
	s_addc_u32 s9, s57, s9
	s_add_i32 s65, s68, s83
	s_mov_b32 s70, m0
	s_mov_b32 m0, s65
	s_nop 0
	global_load_lds_dwordx4 v187, s[8:9]
	s_mov_b32 m0, s70
	s_addk_i32 s65, 0x400
	s_mov_b32 s70, m0
	s_mov_b32 m0, s65
	s_nop 0
	global_load_lds_dwordx4 v186, s[8:9]
	s_mov_b32 m0, s70
	s_ashr_i32 s8, s61, 8
	v_lshl_add_u32 v1, s8, 2, v128
	ds_read_b128 v[96:99], v1
	ds_read_b128 v[100:103], v1 offset:32
	ds_read_b128 v[80:83], v1 offset:128
	ds_read_b128 v[84:87], v1 offset:160
	ds_read_b128 v[104:107], v1 offset:64
	ds_read_b128 v[108:111], v1 offset:96
	ds_read_b128 v[88:91], v1 offset:192
	ds_read_b128 v[92:95], v1 offset:224
	s_add_i32 s8, s61, 0
	v_add3_u32 v1, s8, v197, v196
	v_add3_u32 v6, s8, v198, v196
	v_add3_u32 v7, s8, v199, v196
	v_add3_u32 v8, s8, v200, v196
	s_setprio 1
	ds_read_b128 v[2:5], v1 offset:49152
	ds_read_b128 v[220:223], v1 offset:57344
	ds_read_b128 v[224:227], v6 offset:49152
	ds_read_b128 v[228:231], v6 offset:57344
	ds_read_b128 v[232:235], v7 offset:49152
	s_waitcnt lgkmcnt(4)
	v_mfma_f32_32x32x16_bf16 v[96:111], v[2:5], v[172:175], v[96:111]
	ds_read_b128 v[2:5], v7 offset:57344
	s_waitcnt lgkmcnt(4)
	v_mfma_f32_32x32x16_bf16 v[80:95], v[220:223], v[172:175], v[80:95]
	ds_read_b128 v[220:223], v8 offset:49152
	s_waitcnt lgkmcnt(4)
	v_mfma_f32_32x32x16_bf16 v[96:111], v[224:227], v[168:171], v[96:111]
	ds_read_b128 v[224:227], v8 offset:57344
	s_waitcnt lgkmcnt(4)
	v_mfma_f32_32x32x16_bf16 v[80:95], v[228:231], v[168:171], v[80:95]
	ds_read_b128 v[228:231], v1 offset:49280
	s_waitcnt lgkmcnt(4)
	v_mfma_f32_32x32x16_bf16 v[96:111], v[232:235], v[164:167], v[96:111]
	ds_read_b128 v[232:235], v1 offset:57472
	s_waitcnt lgkmcnt(4)
	v_mfma_f32_32x32x16_bf16 v[80:95], v[2:5], v[164:167], v[80:95]
	ds_read_b128 v[2:5], v6 offset:49280
	s_waitcnt lgkmcnt(4)
	v_mfma_f32_32x32x16_bf16 v[96:111], v[220:223], v[160:163], v[96:111]
	ds_read_b128 v[220:223], v6 offset:57472
	s_waitcnt lgkmcnt(4)
	v_mfma_f32_32x32x16_bf16 v[80:95], v[224:227], v[160:163], v[80:95]
	ds_read_b128 v[224:227], v7 offset:49280
	s_waitcnt lgkmcnt(4)
	v_mfma_f32_32x32x16_bf16 v[96:111], v[228:231], v[156:159], v[96:111]
	ds_read_b128 v[228:231], v7 offset:57472
	s_waitcnt lgkmcnt(4)
	v_mfma_f32_32x32x16_bf16 v[80:95], v[232:235], v[156:159], v[80:95]
	ds_read_b128 v[232:235], v8 offset:49280
	s_waitcnt lgkmcnt(4)
	v_mfma_f32_32x32x16_bf16 v[96:111], v[2:5], v[152:155], v[96:111]
	ds_read_b128 v[2:5], v8 offset:57472
	s_waitcnt lgkmcnt(4)
	v_mfma_f32_32x32x16_bf16 v[80:95], v[220:223], v[152:155], v[80:95]
	s_waitcnt lgkmcnt(3)
	v_mfma_f32_32x32x16_bf16 v[96:111], v[224:227], v[148:151], v[96:111]
	s_waitcnt lgkmcnt(2)
	v_mfma_f32_32x32x16_bf16 v[80:95], v[228:231], v[148:151], v[80:95]
	s_waitcnt lgkmcnt(1)
	v_mfma_f32_32x32x16_bf16 v[96:111], v[232:235], v[144:147], v[96:111]
	s_waitcnt lgkmcnt(0)
	v_mfma_f32_32x32x16_bf16 v[80:95], v[2:5], v[144:147], v[80:95]
	s_setprio 0
	v_add_f32_e32 v1, 0, v215
	v_add_f32_e32 v1, v217, v1
	v_add_f32_e32 v1, v213, v1
	v_add_f32_e32 v1, v216, v1
	v_add_f32_e32 v1, v211, v1
	v_add_f32_e32 v1, v214, v1
	v_add_f32_e32 v1, v210, v1
	v_add_f32_e32 v1, v212, v1
	v_add_f32_e32 v1, v205, v1
	v_add_f32_e32 v1, v208, v1
	v_add_f32_e32 v1, v203, v1
	v_add_f32_e32 v1, v206, v1
	v_exp_f32_e32 v2, v126
	v_add_f32_e32 v1, v202, v1
	v_exp_f32_e32 v12, v127
	v_add_f32_e32 v1, v209, v1
	v_exp_f32_e32 v13, v124
	v_add_f32_e32 v1, v204, v1
	v_exp_f32_e32 v14, v125
	v_add_f32_e32 v1, v207, v1
	v_exp_f32_e32 v15, v122
	v_add_f32_e32 v1, v2, v1
	v_exp_f32_e32 v122, v123
	v_add_f32_e32 v1, v12, v1
	v_exp_f32_e32 v120, v120
	v_add_f32_e32 v1, v13, v1
	v_exp_f32_e32 v121, v121
	v_add_f32_e32 v1, v14, v1
	v_exp_f32_e32 v118, v118
	v_add_f32_e32 v1, v15, v1
	v_exp_f32_e32 v119, v119
	v_add_f32_e32 v1, v122, v1
	v_exp_f32_e32 v116, v116
	v_add_f32_e32 v1, v120, v1
	v_exp_f32_e32 v117, v117
	v_add_f32_e32 v1, v121, v1
	v_exp_f32_e32 v114, v114
	v_add_f32_e32 v1, v118, v1
	v_exp_f32_e32 v115, v115
	v_add_f32_e32 v1, v119, v1
	v_exp_f32_e32 v123, v112
	v_add_f32_e32 v1, v116, v1
	v_exp_f32_e32 v124, v113
	v_add_f32_e32 v1, v117, v1
	v_add_f32_e32 v1, v114, v1
	v_add_f32_e32 v1, v115, v1
	v_add_f32_e32 v1, v123, v1
	v_add_f32_e32 v1, v124, v1
	v_mov_b32_e32 v3, v1
	s_nop 1
	v_permlane32_swap_b32_e32 v1, v3
	v_cvt_pk_bf16_f32 v4, v215, v217
	v_cvt_pk_bf16_f32 v5, v213, v216
	v_cvt_pk_bf16_f32 v6, v211, v214
	v_cvt_pk_bf16_f32 v7, v210, v212
	v_cvt_pk_bf16_f32 v8, v205, v208
	v_cvt_pk_bf16_f32 v9, v203, v206
	v_cvt_pk_bf16_f32 v10, v202, v209
	v_cvt_pk_bf16_f32 v11, v204, v207
	v_cvt_pk_bf16_f32 v12, v2, v12
	v_cvt_pk_bf16_f32 v13, v13, v14
	v_cvt_pk_bf16_f32 v14, v15, v122
	v_cvt_pk_bf16_f32 v15, v120, v121
	v_cvt_pk_bf16_f32 v112, v118, v119
	v_cvt_pk_bf16_f32 v113, v116, v117
	v_cvt_pk_bf16_f32 v114, v114, v115
	v_cvt_pk_bf16_f32 v115, v123, v124
	s_nop 0
	v_add_u32_e32 v2, s53, v193
	ds_read_b64_tr_b16 v[116:117], v2 offset:0
	ds_read_b64_tr_b16 v[118:119], v2 offset:0x800
	ds_read_b64_tr_b16 v[120:121], v2 offset:0x1000
	ds_read_b64_tr_b16 v[122:123], v2 offset:0x1800
	ds_read_b64_tr_b16 v[124:125], v2 offset:0x2000
	ds_read_b64_tr_b16 v[126:127], v2 offset:0x2800
	ds_read_b64_tr_b16 v[132:133], v2 offset:0x3000
	ds_read_b64_tr_b16 v[134:135], v2 offset:0x3800
	s_waitcnt lgkmcnt(6)
	s_nop 0
	v_mfma_f32_32x32x16_bf16 v[16:31], v[4:7], v[116:119], v[16:31]
	ds_read_b64_tr_b16 v[116:117], v2 offset:0x200
	ds_read_b64_tr_b16 v[118:119], v2 offset:0xa00
	s_waitcnt lgkmcnt(6)
	v_mfma_f32_32x32x16_bf16 v[16:31], v[8:11], v[120:123], v[16:31]
	ds_read_b64_tr_b16 v[120:121], v2 offset:0x1200
	ds_read_b64_tr_b16 v[122:123], v2 offset:0x1a00
	s_waitcnt lgkmcnt(6)
	v_mfma_f32_32x32x16_bf16 v[16:31], v[12:15], v[124:127], v[16:31]
	ds_read_b64_tr_b16 v[124:125], v2 offset:0x2200
	ds_read_b64_tr_b16 v[126:127], v2 offset:0x2a00
	s_waitcnt lgkmcnt(6)
	v_mfma_f32_32x32x16_bf16 v[16:31], v[112:115], v[132:135], v[16:31]
	ds_read_b64_tr_b16 v[132:133], v2 offset:0x3200
	ds_read_b64_tr_b16 v[134:135], v2 offset:0x3a00
	s_waitcnt lgkmcnt(6)
	v_mfma_f32_32x32x16_bf16 v[48:63], v[4:7], v[116:119], v[48:63]
	ds_read_b64_tr_b16 v[116:117], v2 offset:0x400
	ds_read_b64_tr_b16 v[118:119], v2 offset:0xc00
	s_waitcnt lgkmcnt(6)
	v_mfma_f32_32x32x16_bf16 v[48:63], v[8:11], v[120:123], v[48:63]
	ds_read_b64_tr_b16 v[120:121], v2 offset:0x1400
	ds_read_b64_tr_b16 v[122:123], v2 offset:0x1c00
	s_waitcnt lgkmcnt(6)
	v_mfma_f32_32x32x16_bf16 v[48:63], v[12:15], v[124:127], v[48:63]
	ds_read_b64_tr_b16 v[124:125], v2 offset:0x2400
	ds_read_b64_tr_b16 v[126:127], v2 offset:0x2c00
	s_waitcnt lgkmcnt(6)
	v_mfma_f32_32x32x16_bf16 v[48:63], v[112:115], v[132:135], v[48:63]
	ds_read_b64_tr_b16 v[132:133], v2 offset:0x3400
	ds_read_b64_tr_b16 v[134:135], v2 offset:0x3c00
	s_waitcnt lgkmcnt(6)
	v_mfma_f32_32x32x16_bf16 v[64:79], v[4:7], v[116:119], v[64:79]
	ds_read_b64_tr_b16 v[116:117], v2 offset:0x600
	ds_read_b64_tr_b16 v[118:119], v2 offset:0xe00
	s_waitcnt lgkmcnt(6)
	v_mfma_f32_32x32x16_bf16 v[64:79], v[8:11], v[120:123], v[64:79]
	ds_read_b64_tr_b16 v[120:121], v2 offset:0x1600
	ds_read_b64_tr_b16 v[122:123], v2 offset:0x1e00
	s_waitcnt lgkmcnt(6)
	v_mfma_f32_32x32x16_bf16 v[64:79], v[12:15], v[124:127], v[64:79]
	ds_read_b64_tr_b16 v[124:125], v2 offset:0x2600
	ds_read_b64_tr_b16 v[126:127], v2 offset:0x2e00
	s_waitcnt lgkmcnt(6)
	v_mfma_f32_32x32x16_bf16 v[64:79], v[112:115], v[132:135], v[64:79]
	ds_read_b64_tr_b16 v[132:133], v2 offset:0x3600
	ds_read_b64_tr_b16 v[134:135], v2 offset:0x3e00
	s_waitcnt lgkmcnt(6)
	v_mfma_f32_32x32x16_bf16 v[32:47], v[4:7], v[116:119], v[32:47]
	s_add_i32 s8, s91, 64
	s_cmp_le_i32 s8, s69
	s_waitcnt lgkmcnt(4)
	v_mfma_f32_32x32x16_bf16 v[32:47], v[8:11], v[120:123], v[32:47]
	s_waitcnt lgkmcnt(2)
	v_mfma_f32_32x32x16_bf16 v[32:47], v[12:15], v[124:127], v[32:47]
	s_waitcnt lgkmcnt(0)
	v_mfma_f32_32x32x16_bf16 v[32:47], v[112:115], v[132:135], v[32:47]
	s_cbranch_scc1 .LBB0_1171
	v_add_u32_e32 v2, 0x4000003b, v130
	v_cmp_gt_u32_e32 vcc, 2.0, v2
	v_add_u32_e32 v2, 27, v130
	s_nop 0
	v_cndmask_b32_e32 v96, v179, v96, vcc
	v_cmp_lt_u32_e32 vcc, s96, v2
	v_add_u32_e32 v2, 58, v130
	s_nop 0
	v_cndmask_b32_e32 v80, v179, v80, vcc
	v_cmp_lt_u32_e32 vcc, s96, v2
	v_add_u32_e32 v2, 26, v130
	s_nop 0
	v_cndmask_b32_e32 v97, v179, v97, vcc
	v_cmp_lt_u32_e32 vcc, s96, v2
	v_add_u32_e32 v2, 57, v130
	s_nop 0
	v_cndmask_b32_e32 v81, v179, v81, vcc
	v_cmp_lt_u32_e32 vcc, s96, v2
	v_add_u32_e32 v2, 25, v130
	s_nop 0
	v_cndmask_b32_e32 v98, v179, v98, vcc
	v_cmp_lt_u32_e32 vcc, s96, v2
	v_add_u32_e32 v2, 56, v130
	s_nop 0
	v_cndmask_b32_e32 v82, v179, v82, vcc
	v_cmp_lt_u32_e32 vcc, s96, v2
	v_add_u32_e32 v2, 24, v130
	s_nop 0
	v_cndmask_b32_e32 v99, v179, v99, vcc
	v_cmp_lt_u32_e32 vcc, s96, v2
	v_add_u32_e32 v2, 51, v130
	s_nop 0
	v_cndmask_b32_e32 v83, v179, v83, vcc
	v_cmp_lt_u32_e32 vcc, s96, v2
	v_add_u32_e32 v2, 19, v130
	s_nop 0
	v_cndmask_b32_e32 v100, v179, v100, vcc
	v_cmp_lt_u32_e32 vcc, s96, v2
	v_add_u32_e32 v2, 50, v130
	s_nop 0
	v_cndmask_b32_e32 v84, v179, v84, vcc
	v_cmp_lt_u32_e32 vcc, s96, v2
	v_add_u32_e32 v2, 18, v130
	s_nop 0
	v_cndmask_b32_e32 v101, v179, v101, vcc
	v_cmp_lt_u32_e32 vcc, s96, v2
	v_add_u32_e32 v2, 49, v130
	s_nop 0
	v_cndmask_b32_e32 v85, v179, v85, vcc
	v_cmp_lt_u32_e32 vcc, s96, v2
	v_add_u32_e32 v2, 17, v130
	s_nop 0
	v_cndmask_b32_e32 v102, v179, v102, vcc
	v_cmp_lt_u32_e32 vcc, s96, v2
	v_add_u32_e32 v2, 48, v130
	s_nop 0
	v_cndmask_b32_e32 v86, v179, v86, vcc
	v_cmp_lt_u32_e32 vcc, s96, v2
	v_add_u32_e32 v2, 16, v130
	s_nop 0
	v_cndmask_b32_e32 v103, v179, v103, vcc
	v_cmp_lt_u32_e32 vcc, s96, v2
	v_add_u32_e32 v2, 43, v130
	s_nop 0
	v_cndmask_b32_e32 v87, v179, v87, vcc
	v_cmp_lt_u32_e32 vcc, s96, v2
	v_add_u32_e32 v2, 11, v130
	s_nop 0
	v_cndmask_b32_e32 v104, v179, v104, vcc
	v_cmp_lt_u32_e32 vcc, s96, v2
	v_add_u32_e32 v2, 42, v130
	s_nop 0
	v_cndmask_b32_e32 v88, v179, v88, vcc
	v_cmp_lt_u32_e32 vcc, s96, v2
	v_add_u32_e32 v2, 10, v130
	s_nop 0
	v_cndmask_b32_e32 v105, v179, v105, vcc
	v_cmp_lt_u32_e32 vcc, s96, v2
	v_add_u32_e32 v2, 41, v130
	s_nop 0
	v_cndmask_b32_e32 v89, v179, v89, vcc
	v_cmp_lt_u32_e32 vcc, s96, v2
	v_add_u32_e32 v2, 9, v130
	s_nop 0
	v_cndmask_b32_e32 v106, v179, v106, vcc
	v_cmp_lt_u32_e32 vcc, s96, v2
	v_add_u32_e32 v2, 40, v130
	s_nop 0
	v_cndmask_b32_e32 v90, v179, v90, vcc
	v_cmp_lt_u32_e32 vcc, s96, v2
	v_add_u32_e32 v2, 8, v130
	s_nop 0
	v_cndmask_b32_e32 v107, v179, v107, vcc
	v_cmp_lt_u32_e32 vcc, s96, v2
	v_add_u32_e32 v2, 35, v130
	s_nop 0
	v_cndmask_b32_e32 v91, v179, v91, vcc
	v_cmp_lt_u32_e32 vcc, s96, v2
	v_add_u32_e32 v2, 3, v130
	s_nop 0
	v_cndmask_b32_e32 v108, v179, v108, vcc
	v_cmp_lt_u32_e32 vcc, s96, v2
	v_add_u32_e32 v2, 34, v130
	s_nop 0
	v_cndmask_b32_e32 v92, v179, v92, vcc
	v_cmp_lt_u32_e32 vcc, s96, v2
	v_add_u32_e32 v2, 2, v130
	s_nop 0
	v_cndmask_b32_e32 v109, v179, v109, vcc
	v_cmp_lt_u32_e32 vcc, s96, v2
	v_add_u32_e32 v2, 33, v130
	s_nop 0
	v_cndmask_b32_e32 v93, v179, v93, vcc
	v_cmp_lt_u32_e32 vcc, s96, v2
	v_add_u32_e32 v2, 1, v130
	s_nop 0
	v_cndmask_b32_e32 v110, v179, v110, vcc
	v_cmp_lt_u32_e32 vcc, s96, v2
	v_add_u32_e32 v2, 32, v130
	s_nop 0
	v_cndmask_b32_e32 v94, v179, v94, vcc
	v_cmp_lt_u32_e32 vcc, s96, v2
	s_nop 1
	v_cndmask_b32_e32 v111, v179, v111, vcc
	v_cmp_lt_u32_e32 vcc, s96, v130
	s_nop 1
	v_cndmask_b32_e32 v95, v179, v95, vcc

.LBB0_1175:
	v_cndmask_b32_e64 v2, v2, v201, s[8:9]
	s_waitcnt vmcnt(5) lgkmcnt(0)
	s_barrier
	s_add_i32 s8, s61, s90
	s_mov_b32 s9, m0
	s_mov_b32 m0, s8
	s_nop 0
	global_load_lds_dwordx4 v183, s[62:63]
	s_mov_b32 m0, s9
	s_addk_i32 s8, 0x400
	s_mov_b32 s9, m0
	s_mov_b32 m0, s8
	s_nop 0
	global_load_lds_dwordx4 v184, s[62:63]
	s_mov_b32 m0, s9
	s_ashr_i32 s8, s61, 6
	s_cmp_lg_u32 0, -1
	s_cselect_b32 s9, 0, 0
	s_add_i32 s8, s9, s8
	s_add_i32 s8, s8, 0x18800
	s_mov_b32 s9, m0
	s_mov_b32 m0, s8
	s_nop 0
	global_load_lds_dword v185, s[0:1]
	s_mov_b32 m0, s9
	s_add_u32 s8, s56, s66
	s_addc_u32 s9, s57, s67
	s_add_i32 s65, s53, s83
	s_mov_b32 s66, m0
	s_mov_b32 m0, s65
	s_nop 0
	global_load_lds_dwordx4 v187, s[8:9]
	s_mov_b32 m0, s66
	s_addk_i32 s65, 0x400
	s_mov_b32 s66, m0
	s_mov_b32 m0, s65
	s_nop 0
	global_load_lds_dwordx4 v186, s[8:9]
	s_mov_b32 m0, s66
	v_mul_f32_e32 v5, 0xbe0293ee, v2
	v_fmamk_f32 v6, v96, 0x3e0293ee, v5
	v_fmamk_f32 v7, v97, 0x3e0293ee, v5
	v_fmamk_f32 v8, v98, 0x3e0293ee, v5
	v_fmamk_f32 v9, v99, 0x3e0293ee, v5
	v_fmamk_f32 v10, v100, 0x3e0293ee, v5
	v_fmamk_f32 v11, v101, 0x3e0293ee, v5
	v_fmamk_f32 v12, v102, 0x3e0293ee, v5
	v_fmamk_f32 v13, v103, 0x3e0293ee, v5
	v_fmamk_f32 v14, v104, 0x3e0293ee, v5
	v_fmamk_f32 v15, v105, 0x3e0293ee, v5
	v_fmamk_f32 v96, v106, 0x3e0293ee, v5
	v_fmamk_f32 v97, v107, 0x3e0293ee, v5
	v_fmamk_f32 v98, v108, 0x3e0293ee, v5
	v_fmamk_f32 v99, v109, 0x3e0293ee, v5
	v_fmamk_f32 v100, v110, 0x3e0293ee, v5
	v_fmamk_f32 v101, v111, 0x3e0293ee, v5
	v_fmamk_f32 v112, v80, 0x3e0293ee, v5
	v_fmamk_f32 v113, v81, 0x3e0293ee, v5
	v_fmamk_f32 v114, v82, 0x3e0293ee, v5
	v_fmamk_f32 v115, v83, 0x3e0293ee, v5
	v_fmamk_f32 v116, v84, 0x3e0293ee, v5
	v_fmamk_f32 v117, v85, 0x3e0293ee, v5
	v_fmamk_f32 v118, v86, 0x3e0293ee, v5
	v_fmamk_f32 v119, v87, 0x3e0293ee, v5
	v_fmamk_f32 v120, v88, 0x3e0293ee, v5
	v_fmamk_f32 v121, v89, 0x3e0293ee, v5
	v_fmamk_f32 v122, v90, 0x3e0293ee, v5
	v_fmamk_f32 v123, v91, 0x3e0293ee, v5
	v_fmamk_f32 v124, v92, 0x3e0293ee, v5
	v_fmamk_f32 v125, v93, 0x3e0293ee, v5
	v_fmamk_f32 v126, v94, 0x3e0293ee, v5
	v_fmac_f32_e32 v5, 0x3e0293ee, v95
	v_exp_f32_e32 v127, v6
	v_exp_f32_e32 v131, v7
	v_exp_f32_e32 v132, v8
	v_exp_f32_e32 v133, v9
	v_exp_f32_e32 v10, v10
	v_exp_f32_e32 v11, v11
	v_exp_f32_e32 v12, v12
	v_exp_f32_e32 v13, v13
	v_exp_f32_e32 v14, v14
	v_exp_f32_e32 v15, v15
	v_exp_f32_e32 v134, v96
	v_exp_f32_e32 v135, v97
	v_exp_f32_e32 v136, v98
	v_exp_f32_e32 v137, v99
	v_exp_f32_e32 v138, v100
	v_exp_f32_e32 v139, v101
	s_ashr_i32 s8, s68, 8
	v_lshl_add_u32 v6, s8, 2, v128
	ds_read_b128 v[96:99], v6
	ds_read_b128 v[100:103], v6 offset:32
	ds_read_b128 v[80:83], v6 offset:128
	ds_read_b128 v[84:87], v6 offset:160
	ds_read_b128 v[104:107], v6 offset:64
	ds_read_b128 v[108:111], v6 offset:96
	ds_read_b128 v[88:91], v6 offset:192
	ds_read_b128 v[92:95], v6 offset:224
	s_add_i32 s8, s68, 0
	v_add3_u32 v140, s8, v197, v196
	v_add3_u32 v141, s8, v198, v196
	v_add3_u32 v142, s8, v199, v196
	v_add3_u32 v143, s8, v200, v196
	s_setprio 1
	ds_read_b128 v[6:9], v140 offset:49152
	ds_read_b128 v[220:223], v140 offset:57344
	ds_read_b128 v[224:227], v141 offset:49152
	ds_read_b128 v[228:231], v141 offset:57344
	ds_read_b128 v[232:235], v142 offset:49152
	s_waitcnt lgkmcnt(4)
	v_mfma_f32_32x32x16_bf16 v[96:111], v[6:9], v[172:175], v[96:111]
	ds_read_b128 v[6:9], v142 offset:57344
	s_waitcnt lgkmcnt(4)
	v_mfma_f32_32x32x16_bf16 v[80:95], v[220:223], v[172:175], v[80:95]
	ds_read_b128 v[220:223], v143 offset:49152
	s_waitcnt lgkmcnt(4)
	v_mfma_f32_32x32x16_bf16 v[96:111], v[224:227], v[168:171], v[96:111]
	ds_read_b128 v[224:227], v143 offset:57344
	s_waitcnt lgkmcnt(4)
	v_mfma_f32_32x32x16_bf16 v[80:95], v[228:231], v[168:171], v[80:95]
	ds_read_b128 v[228:231], v140 offset:49280
	s_waitcnt lgkmcnt(4)
	v_mfma_f32_32x32x16_bf16 v[96:111], v[232:235], v[164:167], v[96:111]
	ds_read_b128 v[232:235], v140 offset:57472
	s_waitcnt lgkmcnt(4)
	v_mfma_f32_32x32x16_bf16 v[80:95], v[6:9], v[164:167], v[80:95]
	ds_read_b128 v[6:9], v141 offset:49280
	s_waitcnt lgkmcnt(4)
	v_mfma_f32_32x32x16_bf16 v[96:111], v[220:223], v[160:163], v[96:111]
	ds_read_b128 v[220:223], v141 offset:57472
	s_waitcnt lgkmcnt(4)
	v_mfma_f32_32x32x16_bf16 v[80:95], v[224:227], v[160:163], v[80:95]
	ds_read_b128 v[224:227], v142 offset:49280
	s_waitcnt lgkmcnt(4)
	v_mfma_f32_32x32x16_bf16 v[96:111], v[228:231], v[156:159], v[96:111]
	ds_read_b128 v[228:231], v142 offset:57472
	s_waitcnt lgkmcnt(4)
	v_mfma_f32_32x32x16_bf16 v[80:95], v[232:235], v[156:159], v[80:95]
	ds_read_b128 v[232:235], v143 offset:49280
	s_waitcnt lgkmcnt(4)
	v_mfma_f32_32x32x16_bf16 v[96:111], v[6:9], v[152:155], v[96:111]
	ds_read_b128 v[6:9], v143 offset:57472
	s_waitcnt lgkmcnt(4)
	v_mfma_f32_32x32x16_bf16 v[80:95], v[220:223], v[152:155], v[80:95]
	s_waitcnt lgkmcnt(3)
	v_mfma_f32_32x32x16_bf16 v[96:111], v[224:227], v[148:151], v[96:111]
	s_waitcnt lgkmcnt(2)
	v_mfma_f32_32x32x16_bf16 v[80:95], v[228:231], v[148:151], v[80:95]
	s_waitcnt lgkmcnt(1)
	v_mfma_f32_32x32x16_bf16 v[96:111], v[232:235], v[144:147], v[96:111]
	s_waitcnt lgkmcnt(0)
	v_mfma_f32_32x32x16_bf16 v[80:95], v[6:9], v[144:147], v[80:95]
	s_setprio 0
	v_exp_f32_e32 v7, v112
	v_exp_f32_e32 v112, v113
	v_exp_f32_e32 v113, v114
	v_exp_f32_e32 v114, v115
	v_exp_f32_e32 v115, v116
	v_exp_f32_e32 v116, v117
	v_exp_f32_e32 v117, v118
	v_exp_f32_e32 v118, v119
	v_exp_f32_e32 v119, v120
	v_exp_f32_e32 v120, v121
	v_exp_f32_e32 v121, v122
	v_exp_f32_e32 v122, v123
	v_exp_f32_e32 v123, v124
	v_exp_f32_e32 v124, v125
	v_exp_f32_e32 v125, v126
	v_exp_f32_e32 v126, v5
	v_add_f32_e32 v5, 0, v127
	v_add_f32_e32 v5, v131, v5
	v_add_f32_e32 v5, v132, v5
	v_add_f32_e32 v5, v133, v5
	v_add_f32_e32 v5, v10, v5
	v_add_f32_e32 v5, v11, v5
	v_add_f32_e32 v5, v12, v5
	v_add_f32_e32 v5, v13, v5
	v_add_f32_e32 v5, v14, v5
	v_add_f32_e32 v5, v15, v5
	v_add_f32_e32 v5, v134, v5
	v_add_f32_e32 v5, v135, v5
	v_add_f32_e32 v5, v136, v5
	v_add_f32_e32 v5, v137, v5
	v_add_f32_e32 v5, v138, v5
	v_add_f32_e32 v5, v139, v5
	v_add_f32_e32 v5, v7, v5
	v_add_f32_e32 v5, v112, v5
	v_add_f32_e32 v5, v113, v5
	v_add_f32_e32 v5, v114, v5
	v_add_f32_e32 v5, v115, v5
	v_add_f32_e32 v5, v116, v5
	v_add_f32_e32 v5, v117, v5
	v_add_f32_e32 v5, v118, v5
	v_add_f32_e32 v5, v119, v5
	v_add_f32_e32 v5, v120, v5
	v_add_f32_e32 v5, v121, v5
	v_add_f32_e32 v5, v122, v5
	v_add_f32_e32 v5, v123, v5
	v_add_f32_e32 v5, v124, v5
	v_add_f32_e32 v5, v125, v5
	v_add_f32_e32 v5, v126, v5
	v_mov_b32_e32 v6, v5
	s_nop 1
	v_permlane32_swap_b32_e32 v5, v6
	v_cvt_pk_bf16_f32 v8, v127, v131
	v_cvt_pk_bf16_f32 v9, v132, v133
	v_cvt_pk_bf16_f32 v10, v10, v11
	v_cvt_pk_bf16_f32 v11, v12, v13
	v_cvt_pk_bf16_f32 v12, v14, v15
	v_cvt_pk_bf16_f32 v13, v134, v135
	v_cvt_pk_bf16_f32 v14, v136, v137
	v_cvt_pk_bf16_f32 v15, v138, v139
	v_cvt_pk_bf16_f32 v112, v7, v112
	v_cvt_pk_bf16_f32 v113, v113, v114
	v_cvt_pk_bf16_f32 v114, v115, v116
	v_cvt_pk_bf16_f32 v115, v117, v118
	v_cvt_pk_bf16_f32 v116, v119, v120
	v_cvt_pk_bf16_f32 v117, v121, v122
	v_cvt_pk_bf16_f32 v118, v123, v124
	v_cvt_pk_bf16_f32 v119, v125, v126
	s_nop 0
	v_add_u32_e32 v7, s61, v193
	ds_read_b64_tr_b16 v[120:121], v7 offset:0
	ds_read_b64_tr_b16 v[122:123], v7 offset:0x800
	ds_read_b64_tr_b16 v[124:125], v7 offset:0x1000
	ds_read_b64_tr_b16 v[126:127], v7 offset:0x1800
	ds_read_b64_tr_b16 v[132:133], v7 offset:0x2000
	ds_read_b64_tr_b16 v[134:135], v7 offset:0x2800
	ds_read_b64_tr_b16 v[136:137], v7 offset:0x3000
	ds_read_b64_tr_b16 v[138:139], v7 offset:0x3800
	s_waitcnt lgkmcnt(6)
	s_nop 0
	v_mfma_f32_32x32x16_bf16 v[16:31], v[8:11], v[120:123], v[16:31]
	ds_read_b64_tr_b16 v[120:121], v7 offset:0x200
	ds_read_b64_tr_b16 v[122:123], v7 offset:0xa00
	s_waitcnt lgkmcnt(6)
	v_mfma_f32_32x32x16_bf16 v[16:31], v[12:15], v[124:127], v[16:31]
	ds_read_b64_tr_b16 v[124:125], v7 offset:0x1200
	ds_read_b64_tr_b16 v[126:127], v7 offset:0x1a00
	s_waitcnt lgkmcnt(6)
	v_mfma_f32_32x32x16_bf16 v[16:31], v[112:115], v[132:135], v[16:31]
	ds_read_b64_tr_b16 v[132:133], v7 offset:0x2200
	ds_read_b64_tr_b16 v[134:135], v7 offset:0x2a00
	s_waitcnt lgkmcnt(6)
	v_mfma_f32_32x32x16_bf16 v[16:31], v[116:119], v[136:139], v[16:31]
	ds_read_b64_tr_b16 v[136:137], v7 offset:0x3200
	ds_read_b64_tr_b16 v[138:139], v7 offset:0x3a00
	s_waitcnt lgkmcnt(6)
	v_mfma_f32_32x32x16_bf16 v[48:63], v[8:11], v[120:123], v[48:63]
	ds_read_b64_tr_b16 v[120:121], v7 offset:0x400
	ds_read_b64_tr_b16 v[122:123], v7 offset:0xc00
	s_waitcnt lgkmcnt(6)
	v_mfma_f32_32x32x16_bf16 v[48:63], v[12:15], v[124:127], v[48:63]
	ds_read_b64_tr_b16 v[124:125], v7 offset:0x1400
	ds_read_b64_tr_b16 v[126:127], v7 offset:0x1c00
	s_waitcnt lgkmcnt(6)
	v_mfma_f32_32x32x16_bf16 v[48:63], v[112:115], v[132:135], v[48:63]
	ds_read_b64_tr_b16 v[132:133], v7 offset:0x2400
	ds_read_b64_tr_b16 v[134:135], v7 offset:0x2c00
	s_waitcnt lgkmcnt(6)
	v_mfma_f32_32x32x16_bf16 v[48:63], v[116:119], v[136:139], v[48:63]
	ds_read_b64_tr_b16 v[136:137], v7 offset:0x3400
	ds_read_b64_tr_b16 v[138:139], v7 offset:0x3c00
	s_waitcnt lgkmcnt(6)
	v_mfma_f32_32x32x16_bf16 v[64:79], v[8:11], v[120:123], v[64:79]
	ds_read_b64_tr_b16 v[120:121], v7 offset:0x600
	ds_read_b64_tr_b16 v[122:123], v7 offset:0xe00
	s_waitcnt lgkmcnt(6)
	v_mfma_f32_32x32x16_bf16 v[64:79], v[12:15], v[124:127], v[64:79]
	ds_read_b64_tr_b16 v[124:125], v7 offset:0x1600
	ds_read_b64_tr_b16 v[126:127], v7 offset:0x1e00
	s_waitcnt lgkmcnt(6)
	v_mfma_f32_32x32x16_bf16 v[64:79], v[112:115], v[132:135], v[64:79]
	ds_read_b64_tr_b16 v[132:133], v7 offset:0x2600
	ds_read_b64_tr_b16 v[134:135], v7 offset:0x2e00
	s_waitcnt lgkmcnt(6)
	v_mfma_f32_32x32x16_bf16 v[64:79], v[116:119], v[136:139], v[64:79]
	ds_read_b64_tr_b16 v[136:137], v7 offset:0x3600
	ds_read_b64_tr_b16 v[138:139], v7 offset:0x3e00
	s_waitcnt lgkmcnt(6)
	v_mfma_f32_32x32x16_bf16 v[32:47], v[8:11], v[120:123], v[32:47]
	s_cmp_le_i32 s91, s69
	s_waitcnt lgkmcnt(4)
	v_mfma_f32_32x32x16_bf16 v[32:47], v[12:15], v[124:127], v[32:47]
	s_waitcnt lgkmcnt(2)
	v_mfma_f32_32x32x16_bf16 v[32:47], v[112:115], v[132:135], v[32:47]
	s_waitcnt lgkmcnt(0)
	v_mfma_f32_32x32x16_bf16 v[32:47], v[116:119], v[136:139], v[32:47]
	s_cbranch_scc1 .LBB0_1177
	v_add_u32_e32 v7, 0x4000007b, v130
	v_cmp_gt_u32_e32 vcc, 2.0, v7
	v_add_u32_e32 v7, 0x5b, v130
	s_nop 0
	v_cndmask_b32_e32 v96, v179, v96, vcc
	v_cmp_lt_u32_e32 vcc, s96, v7
	v_add_u32_e32 v7, 0x7a, v130
	s_nop 0
	v_cndmask_b32_e32 v80, v179, v80, vcc
	v_cmp_lt_u32_e32 vcc, s96, v7
	v_add_u32_e32 v7, 0x5a, v130
	s_nop 0
	v_cndmask_b32_e32 v97, v179, v97, vcc
	v_cmp_lt_u32_e32 vcc, s96, v7
	v_add_u32_e32 v7, 0x79, v130
	s_nop 0
	v_cndmask_b32_e32 v81, v179, v81, vcc
	v_cmp_lt_u32_e32 vcc, s96, v7
	v_add_u32_e32 v7, 0x59, v130
	s_nop 0
	v_cndmask_b32_e32 v98, v179, v98, vcc
	v_cmp_lt_u32_e32 vcc, s96, v7
	v_add_u32_e32 v7, 0x78, v130
	s_nop 0
	v_cndmask_b32_e32 v82, v179, v82, vcc
	v_cmp_lt_u32_e32 vcc, s96, v7
	v_add_u32_e32 v7, 0x58, v130
	s_nop 0
	v_cndmask_b32_e32 v99, v179, v99, vcc
	v_cmp_lt_u32_e32 vcc, s96, v7
	v_add_u32_e32 v7, 0x73, v130
	s_nop 0
	v_cndmask_b32_e32 v83, v179, v83, vcc
	v_cmp_lt_u32_e32 vcc, s96, v7
	v_add_u32_e32 v7, 0x53, v130
	s_nop 0
	v_cndmask_b32_e32 v100, v179, v100, vcc
	v_cmp_lt_u32_e32 vcc, s96, v7
	v_add_u32_e32 v7, 0x72, v130
	s_nop 0
	v_cndmask_b32_e32 v84, v179, v84, vcc
	v_cmp_lt_u32_e32 vcc, s96, v7
	v_add_u32_e32 v7, 0x52, v130
	s_nop 0
	v_cndmask_b32_e32 v101, v179, v101, vcc
	v_cmp_lt_u32_e32 vcc, s96, v7
	v_add_u32_e32 v7, 0x71, v130
	s_nop 0
	v_cndmask_b32_e32 v85, v179, v85, vcc
	v_cmp_lt_u32_e32 vcc, s96, v7
	v_add_u32_e32 v7, 0x51, v130
	s_nop 0
	v_cndmask_b32_e32 v102, v179, v102, vcc
	v_cmp_lt_u32_e32 vcc, s96, v7
	v_add_u32_e32 v7, 0x70, v130
	s_nop 0
	v_cndmask_b32_e32 v86, v179, v86, vcc
	v_cmp_lt_u32_e32 vcc, s96, v7
	v_add_u32_e32 v7, 0x50, v130
	s_nop 0
	v_cndmask_b32_e32 v103, v179, v103, vcc
	v_cmp_lt_u32_e32 vcc, s96, v7
	v_add_u32_e32 v7, 0x6b, v130
	s_nop 0
	v_cndmask_b32_e32 v87, v179, v87, vcc
	v_cmp_lt_u32_e32 vcc, s96, v7
	v_add_u32_e32 v7, 0x4b, v130
	s_nop 0
	v_cndmask_b32_e32 v104, v179, v104, vcc
	v_cmp_lt_u32_e32 vcc, s96, v7
	v_add_u32_e32 v7, 0x6a, v130
	s_nop 0
	v_cndmask_b32_e32 v88, v179, v88, vcc
	v_cmp_lt_u32_e32 vcc, s96, v7
	v_add_u32_e32 v7, 0x4a, v130
	s_nop 0
	v_cndmask_b32_e32 v105, v179, v105, vcc
	v_cmp_lt_u32_e32 vcc, s96, v7
	v_add_u32_e32 v7, 0x69, v130
	s_nop 0
	v_cndmask_b32_e32 v89, v179, v89, vcc
	v_cmp_lt_u32_e32 vcc, s96, v7
	v_add_u32_e32 v7, 0x49, v130
	s_nop 0
	v_cndmask_b32_e32 v106, v179, v106, vcc
	v_cmp_lt_u32_e32 vcc, s96, v7
	v_add_u32_e32 v7, 0x68, v130
	s_nop 0
	v_cndmask_b32_e32 v90, v179, v90, vcc
	v_cmp_lt_u32_e32 vcc, s96, v7
	v_add_u32_e32 v7, 0x48, v130
	s_nop 0
	v_cndmask_b32_e32 v107, v179, v107, vcc
	v_cmp_lt_u32_e32 vcc, s96, v7
	v_add_u32_e32 v7, 0x63, v130
	s_nop 0
	v_cndmask_b32_e32 v91, v179, v91, vcc
	v_cmp_lt_u32_e32 vcc, s96, v7
	v_add_u32_e32 v7, 0x43, v130
	s_nop 0
	v_cndmask_b32_e32 v108, v179, v108, vcc
	v_cmp_lt_u32_e32 vcc, s96, v7
	v_add_u32_e32 v7, 0x62, v130
	s_nop 0
	v_cndmask_b32_e32 v92, v179, v92, vcc
	v_cmp_lt_u32_e32 vcc, s96, v7
	v_add_u32_e32 v7, 0x42, v130
	s_nop 0
	v_cndmask_b32_e32 v109, v179, v109, vcc
	v_cmp_lt_u32_e32 vcc, s96, v7
	v_add_u32_e32 v7, 0x61, v130
	s_nop 0
	v_cndmask_b32_e32 v93, v179, v93, vcc
	v_cmp_lt_u32_e32 vcc, s96, v7
	v_add_u32_e32 v7, 0x41, v130
	s_nop 0
	v_cndmask_b32_e32 v110, v179, v110, vcc
	v_cmp_lt_u32_e32 vcc, s96, v7
	v_add_u32_e32 v7, 0x60, v130
	s_nop 0
	v_cndmask_b32_e32 v94, v179, v94, vcc
	v_cmp_lt_u32_e32 vcc, s96, v7
	v_add_u32_e32 v7, 64, v130
	s_nop 0
	v_cndmask_b32_e32 v111, v179, v111, vcc
	v_cmp_lt_u32_e32 vcc, s96, v7
	s_nop 1
	v_cndmask_b32_e32 v95, v179, v95, vcc

.LBB0_1189:
	s_add_i32 s8, s0, 2
	s_ashr_i32 s9, s8, 31
	s_lshl_b64 s[8:9], s[8:9], 14
	s_add_u32 s8, s56, s8
	s_addc_u32 s9, s57, s9
	s_add_i32 s1, s68, s83
	s_mov_b32 s64, m0
	s_mov_b32 m0, s1
	s_nop 0
	global_load_lds_dwordx4 v187, s[8:9]
	s_mov_b32 m0, s64
	s_addk_i32 s1, 0x400
	s_mov_b32 s64, m0
	s_mov_b32 m0, s1
	s_nop 0
	global_load_lds_dwordx4 v186, s[8:9]
	s_mov_b32 m0, s64
	s_ashr_i32 s1, s66, 8
	v_lshl_add_u32 v2, s1, 2, v128
	ds_read_b128 v[96:99], v2
	ds_read_b128 v[100:103], v2 offset:32
	ds_read_b128 v[80:83], v2 offset:128
	ds_read_b128 v[84:87], v2 offset:160
	ds_read_b128 v[104:107], v2 offset:64
	ds_read_b128 v[108:111], v2 offset:96
	ds_read_b128 v[88:91], v2 offset:192
	ds_read_b128 v[92:95], v2 offset:224
	s_add_i32 s1, s66, 0
	v_add3_u32 v6, s1, v197, v196
	v_add3_u32 v7, s1, v198, v196
	v_add3_u32 v8, s1, v199, v196
	v_add3_u32 v9, s1, v200, v196
	s_setprio 1
	ds_read_b128 v[2:5], v6 offset:49152
	ds_read_b128 v[220:223], v6 offset:57344
	ds_read_b128 v[224:227], v7 offset:49152
	ds_read_b128 v[228:231], v7 offset:57344
	ds_read_b128 v[232:235], v8 offset:49152
	s_waitcnt lgkmcnt(4)
	v_mfma_f32_32x32x16_bf16 v[96:111], v[2:5], v[172:175], v[96:111]
	ds_read_b128 v[2:5], v8 offset:57344
	s_waitcnt lgkmcnt(4)
	v_mfma_f32_32x32x16_bf16 v[80:95], v[220:223], v[172:175], v[80:95]
	ds_read_b128 v[220:223], v9 offset:49152
	s_waitcnt lgkmcnt(4)
	v_mfma_f32_32x32x16_bf16 v[96:111], v[224:227], v[168:171], v[96:111]
	ds_read_b128 v[224:227], v9 offset:57344
	s_waitcnt lgkmcnt(4)
	v_mfma_f32_32x32x16_bf16 v[80:95], v[228:231], v[168:171], v[80:95]
	ds_read_b128 v[228:231], v6 offset:49280
	s_waitcnt lgkmcnt(4)
	v_mfma_f32_32x32x16_bf16 v[96:111], v[232:235], v[164:167], v[96:111]
	ds_read_b128 v[232:235], v6 offset:57472
	s_waitcnt lgkmcnt(4)
	v_mfma_f32_32x32x16_bf16 v[80:95], v[2:5], v[164:167], v[80:95]
	ds_read_b128 v[2:5], v7 offset:49280
	s_waitcnt lgkmcnt(4)
	v_mfma_f32_32x32x16_bf16 v[96:111], v[220:223], v[160:163], v[96:111]
	ds_read_b128 v[220:223], v7 offset:57472
	s_waitcnt lgkmcnt(4)
	v_mfma_f32_32x32x16_bf16 v[80:95], v[224:227], v[160:163], v[80:95]
	ds_read_b128 v[224:227], v8 offset:49280
	s_waitcnt lgkmcnt(4)
	v_mfma_f32_32x32x16_bf16 v[96:111], v[228:231], v[156:159], v[96:111]
	ds_read_b128 v[228:231], v8 offset:57472
	s_waitcnt lgkmcnt(4)
	v_mfma_f32_32x32x16_bf16 v[80:95], v[232:235], v[156:159], v[80:95]
	ds_read_b128 v[232:235], v9 offset:49280
	s_waitcnt lgkmcnt(4)
	v_mfma_f32_32x32x16_bf16 v[96:111], v[2:5], v[152:155], v[96:111]
	ds_read_b128 v[2:5], v9 offset:57472
	s_waitcnt lgkmcnt(4)
	v_mfma_f32_32x32x16_bf16 v[80:95], v[220:223], v[152:155], v[80:95]
	s_waitcnt lgkmcnt(3)
	v_mfma_f32_32x32x16_bf16 v[96:111], v[224:227], v[148:151], v[96:111]
	s_waitcnt lgkmcnt(2)
	v_mfma_f32_32x32x16_bf16 v[80:95], v[228:231], v[148:151], v[80:95]
	s_waitcnt lgkmcnt(1)
	v_mfma_f32_32x32x16_bf16 v[96:111], v[232:235], v[144:147], v[96:111]
	s_waitcnt lgkmcnt(0)
	v_mfma_f32_32x32x16_bf16 v[80:95], v[2:5], v[144:147], v[80:95]
	s_setprio 0
	v_add_f32_e32 v3, 0, v215
	v_add_f32_e32 v3, v217, v3
	v_add_f32_e32 v3, v213, v3
	v_add_f32_e32 v3, v216, v3
	v_add_f32_e32 v3, v211, v3
	v_add_f32_e32 v3, v214, v3
	v_add_f32_e32 v3, v210, v3
	v_add_f32_e32 v3, v212, v3
	v_add_f32_e32 v3, v205, v3
	v_add_f32_e32 v3, v208, v3
	v_add_f32_e32 v3, v203, v3
	v_add_f32_e32 v3, v206, v3
	v_exp_f32_e32 v2, v126
	v_add_f32_e32 v3, v202, v3
	v_exp_f32_e32 v5, v127
	v_add_f32_e32 v3, v209, v3
	v_exp_f32_e32 v14, v124
	v_add_f32_e32 v3, v204, v3
	v_exp_f32_e32 v15, v125
	v_add_f32_e32 v3, v207, v3
	v_exp_f32_e32 v122, v122
	v_add_f32_e32 v3, v2, v3
	v_exp_f32_e32 v123, v123
	v_add_f32_e32 v3, v5, v3
	v_exp_f32_e32 v120, v120
	v_add_f32_e32 v3, v14, v3
	v_exp_f32_e32 v121, v121
	v_add_f32_e32 v3, v15, v3
	v_exp_f32_e32 v118, v118
	v_add_f32_e32 v3, v122, v3
	v_exp_f32_e32 v119, v119
	v_add_f32_e32 v3, v123, v3
	v_exp_f32_e32 v124, v116
	v_add_f32_e32 v3, v120, v3
	v_exp_f32_e32 v117, v117
	v_add_f32_e32 v3, v121, v3
	v_exp_f32_e32 v125, v114
	v_add_f32_e32 v3, v118, v3
	v_exp_f32_e32 v126, v115
	v_add_f32_e32 v3, v119, v3
	v_exp_f32_e32 v127, v112
	v_add_f32_e32 v3, v124, v3
	v_exp_f32_e32 v130, v113
	v_add_f32_e32 v3, v117, v3
	v_add_f32_e32 v3, v125, v3
	v_add_f32_e32 v3, v126, v3
	v_add_f32_e32 v3, v127, v3
	v_add_f32_e32 v3, v130, v3
	v_mov_b32_e32 v4, v3
	s_nop 1
	v_permlane32_swap_b32_e32 v3, v4
	v_cvt_pk_bf16_f32 v6, v215, v217
	v_cvt_pk_bf16_f32 v7, v213, v216
	v_cvt_pk_bf16_f32 v8, v211, v214
	v_cvt_pk_bf16_f32 v9, v210, v212
	v_cvt_pk_bf16_f32 v10, v205, v208
	v_cvt_pk_bf16_f32 v11, v203, v206
	v_cvt_pk_bf16_f32 v12, v202, v209
	v_cvt_pk_bf16_f32 v13, v204, v207
	v_cvt_pk_bf16_f32 v112, v2, v5
	v_cvt_pk_bf16_f32 v113, v14, v15
	v_cvt_pk_bf16_f32 v114, v122, v123
	v_cvt_pk_bf16_f32 v115, v120, v121
	v_cvt_pk_bf16_f32 v116, v118, v119
	v_cvt_pk_bf16_f32 v117, v124, v117
	v_cvt_pk_bf16_f32 v118, v125, v126
	v_cvt_pk_bf16_f32 v119, v127, v130
	s_nop 0
	v_add_u32_e32 v2, s53, v193
	ds_read_b64_tr_b16 v[120:121], v2 offset:0
	ds_read_b64_tr_b16 v[122:123], v2 offset:0x800
	ds_read_b64_tr_b16 v[124:125], v2 offset:0x1000
	ds_read_b64_tr_b16 v[126:127], v2 offset:0x1800
	ds_read_b64_tr_b16 v[130:131], v2 offset:0x2000
	ds_read_b64_tr_b16 v[132:133], v2 offset:0x2800
	ds_read_b64_tr_b16 v[134:135], v2 offset:0x3000
	ds_read_b64_tr_b16 v[136:137], v2 offset:0x3800
	s_waitcnt lgkmcnt(6)
	s_nop 0
	v_mfma_f32_32x32x16_bf16 v[16:31], v[6:9], v[120:123], v[16:31]
	ds_read_b64_tr_b16 v[120:121], v2 offset:0x200
	ds_read_b64_tr_b16 v[122:123], v2 offset:0xa00
	s_waitcnt lgkmcnt(6)
	v_mfma_f32_32x32x16_bf16 v[16:31], v[10:13], v[124:127], v[16:31]
	ds_read_b64_tr_b16 v[124:125], v2 offset:0x1200
	ds_read_b64_tr_b16 v[126:127], v2 offset:0x1a00
	s_waitcnt lgkmcnt(6)
	v_mfma_f32_32x32x16_bf16 v[16:31], v[112:115], v[130:133], v[16:31]
	ds_read_b64_tr_b16 v[130:131], v2 offset:0x2200
	ds_read_b64_tr_b16 v[132:133], v2 offset:0x2a00
	s_waitcnt lgkmcnt(6)
	v_mfma_f32_32x32x16_bf16 v[16:31], v[116:119], v[134:137], v[16:31]
	ds_read_b64_tr_b16 v[134:135], v2 offset:0x3200
	ds_read_b64_tr_b16 v[136:137], v2 offset:0x3a00
	s_waitcnt lgkmcnt(6)
	v_mfma_f32_32x32x16_bf16 v[48:63], v[6:9], v[120:123], v[48:63]
	ds_read_b64_tr_b16 v[120:121], v2 offset:0x400
	ds_read_b64_tr_b16 v[122:123], v2 offset:0xc00
	s_waitcnt lgkmcnt(6)
	v_mfma_f32_32x32x16_bf16 v[48:63], v[10:13], v[124:127], v[48:63]
	ds_read_b64_tr_b16 v[124:125], v2 offset:0x1400
	ds_read_b64_tr_b16 v[126:127], v2 offset:0x1c00
	s_waitcnt lgkmcnt(6)
	v_mfma_f32_32x32x16_bf16 v[48:63], v[112:115], v[130:133], v[48:63]
	ds_read_b64_tr_b16 v[130:131], v2 offset:0x2400
	ds_read_b64_tr_b16 v[132:133], v2 offset:0x2c00
	s_waitcnt lgkmcnt(6)
	v_mfma_f32_32x32x16_bf16 v[48:63], v[116:119], v[134:137], v[48:63]
	ds_read_b64_tr_b16 v[134:135], v2 offset:0x3400
	ds_read_b64_tr_b16 v[136:137], v2 offset:0x3c00
	s_waitcnt lgkmcnt(6)
	v_mfma_f32_32x32x16_bf16 v[64:79], v[6:9], v[120:123], v[64:79]
	ds_read_b64_tr_b16 v[120:121], v2 offset:0x600
	ds_read_b64_tr_b16 v[122:123], v2 offset:0xe00
	s_waitcnt lgkmcnt(6)
	v_mfma_f32_32x32x16_bf16 v[64:79], v[10:13], v[124:127], v[64:79]
	ds_read_b64_tr_b16 v[124:125], v2 offset:0x1600
	ds_read_b64_tr_b16 v[126:127], v2 offset:0x1e00
	s_waitcnt lgkmcnt(6)
	v_mfma_f32_32x32x16_bf16 v[64:79], v[112:115], v[130:133], v[64:79]
	ds_read_b64_tr_b16 v[130:131], v2 offset:0x2600
	ds_read_b64_tr_b16 v[132:133], v2 offset:0x2e00
	s_waitcnt lgkmcnt(6)
	v_mfma_f32_32x32x16_bf16 v[64:79], v[116:119], v[134:137], v[64:79]
	ds_read_b64_tr_b16 v[134:135], v2 offset:0x3600
	ds_read_b64_tr_b16 v[136:137], v2 offset:0x3e00
	s_waitcnt lgkmcnt(6)
	v_mfma_f32_32x32x16_bf16 v[32:47], v[6:9], v[120:123], v[32:47]
	s_add_i32 s1, s70, 64
	s_cmp_le_i32 s1, s69
	s_waitcnt lgkmcnt(4)
	v_mfma_f32_32x32x16_bf16 v[32:47], v[10:13], v[124:127], v[32:47]
	s_waitcnt lgkmcnt(2)
	v_mfma_f32_32x32x16_bf16 v[32:47], v[112:115], v[130:133], v[32:47]
	s_waitcnt lgkmcnt(0)
	v_mfma_f32_32x32x16_bf16 v[32:47], v[116:119], v[134:137], v[32:47]
	s_cbranch_scc1 .LBB0_1191
	v_add_u32_e32 v2, 0x4000003b, v1
	v_cmp_gt_u32_e32 vcc, 2.0, v2
	v_add_u32_e32 v2, 27, v1
	s_nop 0
	v_cndmask_b32_e32 v96, v179, v96, vcc
	v_cmp_lt_u32_e32 vcc, s96, v2
	v_add_u32_e32 v2, 58, v1
	s_nop 0
	v_cndmask_b32_e32 v80, v179, v80, vcc
	v_cmp_lt_u32_e32 vcc, s96, v2
	v_add_u32_e32 v2, 26, v1
	s_nop 0
	v_cndmask_b32_e32 v97, v179, v97, vcc
	v_cmp_lt_u32_e32 vcc, s96, v2
	v_add_u32_e32 v2, 57, v1
	s_nop 0
	v_cndmask_b32_e32 v81, v179, v81, vcc
	v_cmp_lt_u32_e32 vcc, s96, v2
	v_add_u32_e32 v2, 25, v1
	s_nop 0
	v_cndmask_b32_e32 v98, v179, v98, vcc
	v_cmp_lt_u32_e32 vcc, s96, v2
	v_add_u32_e32 v2, 56, v1
	s_nop 0
	v_cndmask_b32_e32 v82, v179, v82, vcc
	v_cmp_lt_u32_e32 vcc, s96, v2
	v_add_u32_e32 v2, 24, v1
	s_nop 0
	v_cndmask_b32_e32 v99, v179, v99, vcc
	v_cmp_lt_u32_e32 vcc, s96, v2
	v_add_u32_e32 v2, 51, v1
	s_nop 0
	v_cndmask_b32_e32 v83, v179, v83, vcc
	v_cmp_lt_u32_e32 vcc, s96, v2
	v_add_u32_e32 v2, 19, v1
	s_nop 0
	v_cndmask_b32_e32 v100, v179, v100, vcc
	v_cmp_lt_u32_e32 vcc, s96, v2
	v_add_u32_e32 v2, 50, v1
	s_nop 0
	v_cndmask_b32_e32 v84, v179, v84, vcc
	v_cmp_lt_u32_e32 vcc, s96, v2
	v_add_u32_e32 v2, 18, v1
	s_nop 0
	v_cndmask_b32_e32 v101, v179, v101, vcc
	v_cmp_lt_u32_e32 vcc, s96, v2
	v_add_u32_e32 v2, 49, v1
	s_nop 0
	v_cndmask_b32_e32 v85, v179, v85, vcc
	v_cmp_lt_u32_e32 vcc, s96, v2
	v_add_u32_e32 v2, 17, v1
	s_nop 0
	v_cndmask_b32_e32 v102, v179, v102, vcc
	v_cmp_lt_u32_e32 vcc, s96, v2
	v_add_u32_e32 v2, 48, v1
	s_nop 0
	v_cndmask_b32_e32 v86, v179, v86, vcc
	v_cmp_lt_u32_e32 vcc, s96, v2
	v_add_u32_e32 v2, 16, v1
	s_nop 0
	v_cndmask_b32_e32 v103, v179, v103, vcc
	v_cmp_lt_u32_e32 vcc, s96, v2
	v_add_u32_e32 v2, 43, v1
	s_nop 0
	v_cndmask_b32_e32 v87, v179, v87, vcc
	v_cmp_lt_u32_e32 vcc, s96, v2
	v_add_u32_e32 v2, 11, v1
	s_nop 0
	v_cndmask_b32_e32 v104, v179, v104, vcc
	v_cmp_lt_u32_e32 vcc, s96, v2
	v_add_u32_e32 v2, 42, v1
	s_nop 0
	v_cndmask_b32_e32 v88, v179, v88, vcc
	v_cmp_lt_u32_e32 vcc, s96, v2
	v_add_u32_e32 v2, 10, v1
	s_nop 0
	v_cndmask_b32_e32 v105, v179, v105, vcc
	v_cmp_lt_u32_e32 vcc, s96, v2
	v_add_u32_e32 v2, 41, v1
	s_nop 0
	v_cndmask_b32_e32 v89, v179, v89, vcc
	v_cmp_lt_u32_e32 vcc, s96, v2
	v_add_u32_e32 v2, 9, v1
	s_nop 0
	v_cndmask_b32_e32 v106, v179, v106, vcc
	v_cmp_lt_u32_e32 vcc, s96, v2
	v_add_u32_e32 v2, 40, v1
	s_nop 0
	v_cndmask_b32_e32 v90, v179, v90, vcc
	v_cmp_lt_u32_e32 vcc, s96, v2
	v_add_u32_e32 v2, 8, v1
	s_nop 0
	v_cndmask_b32_e32 v107, v179, v107, vcc
	v_cmp_lt_u32_e32 vcc, s96, v2
	v_add_u32_e32 v2, 35, v1
	s_nop 0
	v_cndmask_b32_e32 v91, v179, v91, vcc
	v_cmp_lt_u32_e32 vcc, s96, v2
	v_add_u32_e32 v2, 3, v1
	s_nop 0
	v_cndmask_b32_e32 v108, v179, v108, vcc
	v_cmp_lt_u32_e32 vcc, s96, v2
	v_add_u32_e32 v2, 34, v1
	s_nop 0
	v_cndmask_b32_e32 v92, v179, v92, vcc
	v_cmp_lt_u32_e32 vcc, s96, v2
	v_add_u32_e32 v2, 2, v1
	s_nop 0
	v_cndmask_b32_e32 v109, v179, v109, vcc
	v_cmp_lt_u32_e32 vcc, s96, v2
	v_add_u32_e32 v2, 33, v1
	s_nop 0
	v_cndmask_b32_e32 v93, v179, v93, vcc
	v_cmp_lt_u32_e32 vcc, s96, v2
	v_add_u32_e32 v2, 1, v1
	s_nop 0
	v_cndmask_b32_e32 v110, v179, v110, vcc
	v_cmp_lt_u32_e32 vcc, s96, v2
	v_add_u32_e32 v2, 32, v1
	s_nop 0
	v_cndmask_b32_e32 v94, v179, v94, vcc
	v_cmp_lt_u32_e32 vcc, s96, v2
	s_nop 1
	v_cndmask_b32_e32 v111, v179, v111, vcc
	v_cmp_lt_u32_e32 vcc, s96, v1
	s_nop 1
	v_cndmask_b32_e32 v95, v179, v95, vcc

.LBB0_1200:
	v_cndmask_b32_e64 v2, v2, v201, s[8:9]
	v_mul_f32_e32 v5, 0xbe0293ee, v2
	v_fmamk_f32 v7, v96, 0x3e0293ee, v5
	v_fmamk_f32 v8, v97, 0x3e0293ee, v5
	v_fmamk_f32 v9, v98, 0x3e0293ee, v5
	v_fmamk_f32 v10, v99, 0x3e0293ee, v5
	v_fmamk_f32 v11, v100, 0x3e0293ee, v5
	v_fmamk_f32 v12, v101, 0x3e0293ee, v5
	v_fmamk_f32 v13, v102, 0x3e0293ee, v5
	v_fmamk_f32 v14, v103, 0x3e0293ee, v5
	v_fmamk_f32 v15, v104, 0x3e0293ee, v5
	v_fmamk_f32 v96, v105, 0x3e0293ee, v5
	v_fmamk_f32 v97, v106, 0x3e0293ee, v5
	v_fmamk_f32 v98, v107, 0x3e0293ee, v5
	v_fmamk_f32 v99, v108, 0x3e0293ee, v5
	v_fmamk_f32 v100, v109, 0x3e0293ee, v5
	v_fmamk_f32 v101, v110, 0x3e0293ee, v5
	v_fmamk_f32 v102, v111, 0x3e0293ee, v5
	v_exp_f32_e32 v125, v7
	v_fmamk_f32 v7, v93, 0x3e0293ee, v5
	v_fmamk_f32 v112, v80, 0x3e0293ee, v5
	v_fmamk_f32 v113, v81, 0x3e0293ee, v5
	v_fmamk_f32 v114, v82, 0x3e0293ee, v5
	v_fmamk_f32 v115, v83, 0x3e0293ee, v5
	v_fmamk_f32 v116, v84, 0x3e0293ee, v5
	v_fmamk_f32 v117, v85, 0x3e0293ee, v5
	v_fmamk_f32 v118, v86, 0x3e0293ee, v5
	v_fmamk_f32 v119, v87, 0x3e0293ee, v5
	v_fmamk_f32 v120, v88, 0x3e0293ee, v5
	v_fmamk_f32 v121, v89, 0x3e0293ee, v5
	v_fmamk_f32 v122, v90, 0x3e0293ee, v5
	v_fmamk_f32 v123, v91, 0x3e0293ee, v5
	v_fmamk_f32 v124, v92, 0x3e0293ee, v5
	v_exp_f32_e32 v126, v8
	v_exp_f32_e32 v127, v9
	v_exp_f32_e32 v130, v10
	v_exp_f32_e32 v131, v11
	v_exp_f32_e32 v12, v12
	v_exp_f32_e32 v13, v13
	v_exp_f32_e32 v14, v14
	v_exp_f32_e32 v15, v15
	v_exp_f32_e32 v132, v96
	v_exp_f32_e32 v133, v97
	v_exp_f32_e32 v134, v98
	v_exp_f32_e32 v135, v99
	v_exp_f32_e32 v136, v100
	v_exp_f32_e32 v137, v101
	v_exp_f32_e32 v138, v102
	v_fmamk_f32 v139, v94, 0x3e0293ee, v5
	v_fmac_f32_e32 v5, 0x3e0293ee, v95
	s_ashr_i32 s1, s68, 8
	v_lshl_add_u32 v8, s1, 2, v128
	ds_read_b128 v[96:99], v8
	ds_read_b128 v[100:103], v8 offset:32
	ds_read_b128 v[80:83], v8 offset:128
	ds_read_b128 v[84:87], v8 offset:160
	ds_read_b128 v[104:107], v8 offset:64
	ds_read_b128 v[108:111], v8 offset:96
	ds_read_b128 v[88:91], v8 offset:192
	ds_read_b128 v[92:95], v8 offset:224
	s_add_i32 s1, s68, 0
	v_add3_u32 v140, s1, v197, v196
	v_add3_u32 v141, s1, v198, v196
	v_add3_u32 v142, s1, v199, v196
	v_add3_u32 v143, s1, v200, v196
	s_setprio 1
	ds_read_b128 v[8:11], v140 offset:49152
	ds_read_b128 v[220:223], v140 offset:57344
	ds_read_b128 v[224:227], v141 offset:49152
	ds_read_b128 v[228:231], v141 offset:57344
	ds_read_b128 v[232:235], v142 offset:49152
	s_waitcnt lgkmcnt(4)
	v_mfma_f32_32x32x16_bf16 v[96:111], v[8:11], v[172:175], v[96:111]
	ds_read_b128 v[8:11], v142 offset:57344
	s_waitcnt lgkmcnt(4)
	v_mfma_f32_32x32x16_bf16 v[80:95], v[220:223], v[172:175], v[80:95]
	ds_read_b128 v[220:223], v143 offset:49152
	s_waitcnt lgkmcnt(4)
	v_mfma_f32_32x32x16_bf16 v[96:111], v[224:227], v[168:171], v[96:111]
	ds_read_b128 v[224:227], v143 offset:57344
	s_waitcnt lgkmcnt(4)
	v_mfma_f32_32x32x16_bf16 v[80:95], v[228:231], v[168:171], v[80:95]
	ds_read_b128 v[228:231], v140 offset:49280
	s_waitcnt lgkmcnt(4)
	v_mfma_f32_32x32x16_bf16 v[96:111], v[232:235], v[164:167], v[96:111]
	ds_read_b128 v[232:235], v140 offset:57472
	s_waitcnt lgkmcnt(4)
	v_mfma_f32_32x32x16_bf16 v[80:95], v[8:11], v[164:167], v[80:95]
	ds_read_b128 v[8:11], v141 offset:49280
	s_waitcnt lgkmcnt(4)
	v_mfma_f32_32x32x16_bf16 v[96:111], v[220:223], v[160:163], v[96:111]
	ds_read_b128 v[220:223], v141 offset:57472
	s_waitcnt lgkmcnt(4)
	v_mfma_f32_32x32x16_bf16 v[80:95], v[224:227], v[160:163], v[80:95]
	ds_read_b128 v[224:227], v142 offset:49280
	s_waitcnt lgkmcnt(4)
	v_mfma_f32_32x32x16_bf16 v[96:111], v[228:231], v[156:159], v[96:111]
	ds_read_b128 v[228:231], v142 offset:57472
	s_waitcnt lgkmcnt(4)
	v_mfma_f32_32x32x16_bf16 v[80:95], v[232:235], v[156:159], v[80:95]
	ds_read_b128 v[232:235], v143 offset:49280
	s_waitcnt lgkmcnt(4)
	v_mfma_f32_32x32x16_bf16 v[96:111], v[8:11], v[152:155], v[96:111]
	ds_read_b128 v[8:11], v143 offset:57472
	s_waitcnt lgkmcnt(4)
	v_mfma_f32_32x32x16_bf16 v[80:95], v[220:223], v[152:155], v[80:95]
	s_waitcnt lgkmcnt(3)
	v_mfma_f32_32x32x16_bf16 v[96:111], v[224:227], v[148:151], v[96:111]
	s_waitcnt lgkmcnt(2)
	v_mfma_f32_32x32x16_bf16 v[80:95], v[228:231], v[148:151], v[80:95]
	s_waitcnt lgkmcnt(1)
	v_mfma_f32_32x32x16_bf16 v[96:111], v[232:235], v[144:147], v[96:111]
	s_waitcnt lgkmcnt(0)
	v_mfma_f32_32x32x16_bf16 v[80:95], v[8:11], v[144:147], v[80:95]
	s_setprio 0
	v_exp_f32_e32 v203, v7
	v_add_f32_e32 v7, 0, v125
	v_add_f32_e32 v7, v126, v7
	v_add_f32_e32 v7, v127, v7
	v_add_f32_e32 v7, v130, v7
	v_add_f32_e32 v7, v131, v7
	v_add_f32_e32 v7, v12, v7
	v_add_f32_e32 v7, v13, v7
	v_add_f32_e32 v7, v14, v7
	v_add_f32_e32 v7, v15, v7
	v_add_f32_e32 v7, v132, v7
	v_add_f32_e32 v7, v133, v7
	v_add_f32_e32 v7, v134, v7
	v_exp_f32_e32 v9, v112
	v_add_f32_e32 v7, v135, v7
	v_exp_f32_e32 v140, v113
	v_add_f32_e32 v7, v136, v7
	v_exp_f32_e32 v141, v114
	v_add_f32_e32 v7, v137, v7
	v_exp_f32_e32 v142, v115
	v_add_f32_e32 v7, v138, v7
	v_exp_f32_e32 v143, v116
	v_add_f32_e32 v7, v9, v7
	v_exp_f32_e32 v201, v117
	v_add_f32_e32 v7, v140, v7
	v_exp_f32_e32 v202, v118
	v_add_f32_e32 v7, v141, v7
	v_exp_f32_e32 v119, v119
	v_add_f32_e32 v7, v142, v7
	v_exp_f32_e32 v120, v120
	v_add_f32_e32 v7, v143, v7
	v_exp_f32_e32 v121, v121
	v_add_f32_e32 v7, v201, v7
	v_exp_f32_e32 v122, v122
	v_add_f32_e32 v7, v202, v7
	v_exp_f32_e32 v123, v123
	v_add_f32_e32 v7, v119, v7
	v_exp_f32_e32 v124, v124
	v_add_f32_e32 v7, v120, v7
	v_add_f32_e32 v7, v121, v7
	v_exp_f32_e32 v139, v139
	v_add_f32_e32 v7, v122, v7
	v_exp_f32_e32 v5, v5
	v_add_f32_e32 v7, v123, v7
	v_add_f32_e32 v7, v124, v7
	v_add_f32_e32 v7, v203, v7
	v_add_f32_e32 v7, v139, v7
	v_add_f32_e32 v7, v5, v7
	v_mov_b32_e32 v8, v7
	s_nop 1
	v_permlane32_swap_b32_e32 v7, v8
	v_cvt_pk_bf16_f32 v10, v125, v126
	v_cvt_pk_bf16_f32 v11, v127, v130
	v_cvt_pk_bf16_f32 v12, v131, v12
	v_cvt_pk_bf16_f32 v13, v13, v14
	v_cvt_pk_bf16_f32 v112, v15, v132
	v_cvt_pk_bf16_f32 v113, v133, v134
	v_cvt_pk_bf16_f32 v114, v135, v136
	v_cvt_pk_bf16_f32 v115, v137, v138
	v_cvt_pk_bf16_f32 v116, v9, v140
	v_cvt_pk_bf16_f32 v117, v141, v142
	v_cvt_pk_bf16_f32 v118, v143, v201
	v_cvt_pk_bf16_f32 v119, v202, v119
	v_cvt_pk_bf16_f32 v120, v120, v121
	v_cvt_pk_bf16_f32 v121, v122, v123
	v_cvt_pk_bf16_f32 v122, v124, v203
	v_cvt_pk_bf16_f32 v123, v139, v5
	s_nop 0
	v_add_u32_e32 v5, s66, v193
	ds_read_b64_tr_b16 v[124:125], v5 offset:0
	ds_read_b64_tr_b16 v[126:127], v5 offset:0x800
	ds_read_b64_tr_b16 v[130:131], v5 offset:0x1000
	ds_read_b64_tr_b16 v[132:133], v5 offset:0x1800
	ds_read_b64_tr_b16 v[134:135], v5 offset:0x2000
	ds_read_b64_tr_b16 v[136:137], v5 offset:0x2800
	ds_read_b64_tr_b16 v[138:139], v5 offset:0x3000
	ds_read_b64_tr_b16 v[140:141], v5 offset:0x3800
	s_waitcnt lgkmcnt(6)
	s_nop 0
	v_mfma_f32_32x32x16_bf16 v[16:31], v[10:13], v[124:127], v[16:31]
	ds_read_b64_tr_b16 v[124:125], v5 offset:0x200
	ds_read_b64_tr_b16 v[126:127], v5 offset:0xa00
	s_waitcnt lgkmcnt(6)
	v_mfma_f32_32x32x16_bf16 v[16:31], v[112:115], v[130:133], v[16:31]
	ds_read_b64_tr_b16 v[130:131], v5 offset:0x1200
	ds_read_b64_tr_b16 v[132:133], v5 offset:0x1a00
	s_waitcnt lgkmcnt(6)
	v_mfma_f32_32x32x16_bf16 v[16:31], v[116:119], v[134:137], v[16:31]
	ds_read_b64_tr_b16 v[134:135], v5 offset:0x2200
	ds_read_b64_tr_b16 v[136:137], v5 offset:0x2a00
	s_waitcnt lgkmcnt(6)
	v_mfma_f32_32x32x16_bf16 v[16:31], v[120:123], v[138:141], v[16:31]
	ds_read_b64_tr_b16 v[138:139], v5 offset:0x3200
	ds_read_b64_tr_b16 v[140:141], v5 offset:0x3a00
	s_waitcnt lgkmcnt(6)
	v_mfma_f32_32x32x16_bf16 v[48:63], v[10:13], v[124:127], v[48:63]
	ds_read_b64_tr_b16 v[124:125], v5 offset:0x400
	ds_read_b64_tr_b16 v[126:127], v5 offset:0xc00
	s_waitcnt lgkmcnt(6)
	v_mfma_f32_32x32x16_bf16 v[48:63], v[112:115], v[130:133], v[48:63]
	ds_read_b64_tr_b16 v[130:131], v5 offset:0x1400
	ds_read_b64_tr_b16 v[132:133], v5 offset:0x1c00
	s_waitcnt lgkmcnt(6)
	v_mfma_f32_32x32x16_bf16 v[48:63], v[116:119], v[134:137], v[48:63]
	ds_read_b64_tr_b16 v[134:135], v5 offset:0x2400
	ds_read_b64_tr_b16 v[136:137], v5 offset:0x2c00
	s_waitcnt lgkmcnt(6)
	v_mfma_f32_32x32x16_bf16 v[48:63], v[120:123], v[138:141], v[48:63]
	ds_read_b64_tr_b16 v[138:139], v5 offset:0x3400
	ds_read_b64_tr_b16 v[140:141], v5 offset:0x3c00
	s_waitcnt lgkmcnt(6)
	v_mfma_f32_32x32x16_bf16 v[64:79], v[10:13], v[124:127], v[64:79]
	ds_read_b64_tr_b16 v[124:125], v5 offset:0x600
	ds_read_b64_tr_b16 v[126:127], v5 offset:0xe00
	s_waitcnt lgkmcnt(6)
	v_mfma_f32_32x32x16_bf16 v[64:79], v[112:115], v[130:133], v[64:79]
	ds_read_b64_tr_b16 v[130:131], v5 offset:0x1600
	ds_read_b64_tr_b16 v[132:133], v5 offset:0x1e00
	s_waitcnt lgkmcnt(6)
	v_mfma_f32_32x32x16_bf16 v[64:79], v[116:119], v[134:137], v[64:79]
	ds_read_b64_tr_b16 v[134:135], v5 offset:0x2600
	ds_read_b64_tr_b16 v[136:137], v5 offset:0x2e00
	s_waitcnt lgkmcnt(6)
	v_mfma_f32_32x32x16_bf16 v[64:79], v[120:123], v[138:141], v[64:79]
	ds_read_b64_tr_b16 v[138:139], v5 offset:0x3600
	ds_read_b64_tr_b16 v[140:141], v5 offset:0x3e00
	s_waitcnt lgkmcnt(6)
	v_mfma_f32_32x32x16_bf16 v[32:47], v[10:13], v[124:127], v[32:47]
	s_cmp_le_i32 s70, s69
	s_waitcnt lgkmcnt(4)
	v_mfma_f32_32x32x16_bf16 v[32:47], v[112:115], v[130:133], v[32:47]
	s_waitcnt lgkmcnt(2)
	v_mfma_f32_32x32x16_bf16 v[32:47], v[116:119], v[134:137], v[32:47]
	s_waitcnt lgkmcnt(0)
	v_mfma_f32_32x32x16_bf16 v[32:47], v[120:123], v[138:141], v[32:47]
	s_cbranch_scc1 .LBB0_1202
	v_add_u32_e32 v5, 0x4000007b, v1
	v_cmp_gt_u32_e32 vcc, 2.0, v5
	v_add_u32_e32 v5, 0x5b, v1
	s_nop 0
	v_cndmask_b32_e32 v96, v179, v96, vcc
	v_cmp_lt_u32_e32 vcc, s96, v5
	v_add_u32_e32 v5, 0x7a, v1
	s_nop 0
	v_cndmask_b32_e32 v80, v179, v80, vcc
	v_cmp_lt_u32_e32 vcc, s96, v5
	v_add_u32_e32 v5, 0x5a, v1
	s_nop 0
	v_cndmask_b32_e32 v97, v179, v97, vcc
	v_cmp_lt_u32_e32 vcc, s96, v5
	v_add_u32_e32 v5, 0x79, v1
	s_nop 0
	v_cndmask_b32_e32 v81, v179, v81, vcc
	v_cmp_lt_u32_e32 vcc, s96, v5
	v_add_u32_e32 v5, 0x59, v1
	s_nop 0
	v_cndmask_b32_e32 v98, v179, v98, vcc
	v_cmp_lt_u32_e32 vcc, s96, v5
	v_add_u32_e32 v5, 0x78, v1
	s_nop 0
	v_cndmask_b32_e32 v82, v179, v82, vcc
	v_cmp_lt_u32_e32 vcc, s96, v5
	v_add_u32_e32 v5, 0x58, v1
	s_nop 0
	v_cndmask_b32_e32 v99, v179, v99, vcc
	v_cmp_lt_u32_e32 vcc, s96, v5
	v_add_u32_e32 v5, 0x73, v1
	s_nop 0
	v_cndmask_b32_e32 v83, v179, v83, vcc
	v_cmp_lt_u32_e32 vcc, s96, v5
	v_add_u32_e32 v5, 0x53, v1
	s_nop 0
	v_cndmask_b32_e32 v100, v179, v100, vcc
	v_cmp_lt_u32_e32 vcc, s96, v5
	v_add_u32_e32 v5, 0x72, v1
	s_nop 0
	v_cndmask_b32_e32 v84, v179, v84, vcc
	v_cmp_lt_u32_e32 vcc, s96, v5
	v_add_u32_e32 v5, 0x52, v1
	s_nop 0
	v_cndmask_b32_e32 v101, v179, v101, vcc
	v_cmp_lt_u32_e32 vcc, s96, v5
	v_add_u32_e32 v5, 0x71, v1
	s_nop 0
	v_cndmask_b32_e32 v85, v179, v85, vcc
	v_cmp_lt_u32_e32 vcc, s96, v5
	v_add_u32_e32 v5, 0x51, v1
	s_nop 0
	v_cndmask_b32_e32 v102, v179, v102, vcc
	v_cmp_lt_u32_e32 vcc, s96, v5
	v_add_u32_e32 v5, 0x70, v1
	s_nop 0
	v_cndmask_b32_e32 v86, v179, v86, vcc
	v_cmp_lt_u32_e32 vcc, s96, v5
	v_add_u32_e32 v5, 0x50, v1
	s_nop 0
	v_cndmask_b32_e32 v103, v179, v103, vcc
	v_cmp_lt_u32_e32 vcc, s96, v5
	v_add_u32_e32 v5, 0x6b, v1
	s_nop 0
	v_cndmask_b32_e32 v87, v179, v87, vcc
	v_cmp_lt_u32_e32 vcc, s96, v5
	v_add_u32_e32 v5, 0x4b, v1
	s_nop 0
	v_cndmask_b32_e32 v104, v179, v104, vcc
	v_cmp_lt_u32_e32 vcc, s96, v5
	v_add_u32_e32 v5, 0x6a, v1
	s_nop 0
	v_cndmask_b32_e32 v88, v179, v88, vcc
	v_cmp_lt_u32_e32 vcc, s96, v5
	v_add_u32_e32 v5, 0x4a, v1
	s_nop 0
	v_cndmask_b32_e32 v105, v179, v105, vcc
	v_cmp_lt_u32_e32 vcc, s96, v5
	v_add_u32_e32 v5, 0x69, v1
	s_nop 0
	v_cndmask_b32_e32 v89, v179, v89, vcc
	v_cmp_lt_u32_e32 vcc, s96, v5
	v_add_u32_e32 v5, 0x49, v1
	s_nop 0
	v_cndmask_b32_e32 v106, v179, v106, vcc
	v_cmp_lt_u32_e32 vcc, s96, v5
	v_add_u32_e32 v5, 0x68, v1
	s_nop 0
	v_cndmask_b32_e32 v90, v179, v90, vcc
	v_cmp_lt_u32_e32 vcc, s96, v5
	v_add_u32_e32 v5, 0x48, v1
	s_nop 0
	v_cndmask_b32_e32 v107, v179, v107, vcc
	v_cmp_lt_u32_e32 vcc, s96, v5
	v_add_u32_e32 v5, 0x63, v1
	s_nop 0
	v_cndmask_b32_e32 v91, v179, v91, vcc
	v_cmp_lt_u32_e32 vcc, s96, v5
	v_add_u32_e32 v5, 0x43, v1
	s_nop 0
	v_cndmask_b32_e32 v108, v179, v108, vcc
	v_cmp_lt_u32_e32 vcc, s96, v5
	v_add_u32_e32 v5, 0x62, v1
	s_nop 0
	v_cndmask_b32_e32 v92, v179, v92, vcc
	v_cmp_lt_u32_e32 vcc, s96, v5
	v_add_u32_e32 v5, 0x42, v1
	s_nop 0
	v_cndmask_b32_e32 v109, v179, v109, vcc
	v_cmp_lt_u32_e32 vcc, s96, v5
	v_add_u32_e32 v5, 0x61, v1
	s_nop 0
	v_cndmask_b32_e32 v93, v179, v93, vcc
	v_cmp_lt_u32_e32 vcc, s96, v5
	v_add_u32_e32 v5, 0x41, v1
	s_nop 0
	v_cndmask_b32_e32 v110, v179, v110, vcc
	v_cmp_lt_u32_e32 vcc, s96, v5
	v_add_u32_e32 v5, 0x60, v1
	s_nop 0
	v_cndmask_b32_e32 v94, v179, v94, vcc
	v_cmp_lt_u32_e32 vcc, s96, v5
	v_add_u32_e32 v5, 64, v1
	s_nop 0
	v_cndmask_b32_e32 v111, v179, v111, vcc
	v_cmp_lt_u32_e32 vcc, s96, v5
	s_nop 1
	v_cndmask_b32_e32 v95, v179, v95, vcc

.LBB0_1216:
	v_exp_f32_e32 v13, v126
	v_exp_f32_e32 v14, v127
	v_exp_f32_e32 v15, v124
	v_exp_f32_e32 v218, v125
	v_exp_f32_e32 v219, v122
	v_exp_f32_e32 v220, v123
	v_exp_f32_e32 v221, v120
	v_exp_f32_e32 v222, v121
	v_exp_f32_e32 v4, v118
	v_exp_f32_e32 v223, v119
	v_exp_f32_e32 v252, v116
	v_exp_f32_e32 v253, v117
	v_exp_f32_e32 v254, v114
	v_exp_f32_e32 v10, v115
	v_exp_f32_e32 v11, v112
	v_exp_f32_e32 v12, v113
	v_add_f32_e32 v1, 0, v215
	s_mov_b64 s[0:1], -1
	s_cmp_ge_i32 s67, s12
	v_add_u32_e32 v3, s8, v193
	v_add_f32_e32 v2, v217, v1
	s_cbranch_scc0 .LBB0_1218
	v_add_f32_e32 v1, v213, v2
	v_add_f32_e32 v1, v216, v1
	v_add_f32_e32 v1, v211, v1
	v_add_f32_e32 v1, v214, v1
	v_add_f32_e32 v1, v210, v1
	v_add_f32_e32 v1, v212, v1
	v_add_f32_e32 v1, v205, v1
	v_add_f32_e32 v1, v208, v1
	v_add_f32_e32 v1, v203, v1
	v_add_f32_e32 v1, v206, v1
	v_add_f32_e32 v1, v202, v1
	v_add_f32_e32 v1, v209, v1
	v_add_f32_e32 v1, v204, v1
	v_add_f32_e32 v1, v207, v1
	v_add_f32_e32 v1, v13, v1
	v_add_f32_e32 v1, v14, v1
	v_add_f32_e32 v1, v15, v1
	v_add_f32_e32 v1, v218, v1
	v_add_f32_e32 v1, v219, v1
	v_add_f32_e32 v1, v220, v1
	v_add_f32_e32 v1, v221, v1
	v_add_f32_e32 v1, v222, v1
	v_add_f32_e32 v1, v4, v1
	v_add_f32_e32 v1, v223, v1
	v_add_f32_e32 v1, v252, v1
	v_add_f32_e32 v1, v253, v1
	v_add_f32_e32 v1, v254, v1
	v_add_f32_e32 v1, v10, v1
	v_add_f32_e32 v1, v11, v1
	v_add_f32_e32 v1, v12, v1
	v_mov_b32_e32 v6, v1
	s_nop 1
	v_permlane32_swap_b32_e32 v1, v6
	v_add_f32_e32 v1, v1, v6
	v_fmac_f32_e32 v1, v194, v5
	v_cvt_pk_bf16_f32 v224, v215, v217
	v_cvt_pk_bf16_f32 v225, v213, v216
	v_cvt_pk_bf16_f32 v226, v211, v214
	v_cvt_pk_bf16_f32 v227, v210, v212
	v_cvt_pk_bf16_f32 v228, v205, v208
	v_cvt_pk_bf16_f32 v229, v203, v206
	v_cvt_pk_bf16_f32 v230, v202, v209
	v_cvt_pk_bf16_f32 v231, v204, v207
	v_cvt_pk_bf16_f32 v232, v13, v14
	v_cvt_pk_bf16_f32 v233, v15, v218
	v_cvt_pk_bf16_f32 v234, v219, v220
	v_cvt_pk_bf16_f32 v235, v221, v222
	v_cvt_pk_bf16_f32 v236, v4, v223
	v_cvt_pk_bf16_f32 v237, v252, v253
	v_cvt_pk_bf16_f32 v238, v254, v10
	v_cvt_pk_bf16_f32 v239, v11, v12
	s_nop 0
	ds_read_b64_tr_b16 v[96:97], v3 offset:0
	ds_read_b64_tr_b16 v[98:99], v3 offset:0x800
	ds_read_b64_tr_b16 v[100:101], v3 offset:0x1000
	ds_read_b64_tr_b16 v[102:103], v3 offset:0x1800
	ds_read_b64_tr_b16 v[104:105], v3 offset:0x2000
	ds_read_b64_tr_b16 v[106:107], v3 offset:0x2800
	ds_read_b64_tr_b16 v[108:109], v3 offset:0x3000
	ds_read_b64_tr_b16 v[110:111], v3 offset:0x3800
	s_waitcnt lgkmcnt(6)
	s_nop 0
	v_mfma_f32_32x32x16_bf16 v[80:95], v[224:227], v[96:99], v[16:31]
	ds_read_b64_tr_b16 v[112:113], v3 offset:0x200
	ds_read_b64_tr_b16 v[114:115], v3 offset:0xa00
	ds_read_b64_tr_b16 v[116:117], v3 offset:0x1200
	ds_read_b64_tr_b16 v[118:119], v3 offset:0x1a00
	ds_read_b64_tr_b16 v[120:121], v3 offset:0x2200
	ds_read_b64_tr_b16 v[122:123], v3 offset:0x2a00
	ds_read_b64_tr_b16 v[124:125], v3 offset:0x3200
	s_waitcnt lgkmcnt(6)
	v_mfma_f32_32x32x16_bf16 v[80:95], v[228:231], v[100:103], v[80:95]
	ds_read_b64_tr_b16 v[126:127], v3 offset:0x3a00
	s_waitcnt lgkmcnt(6)
	v_mfma_f32_32x32x16_bf16 v[80:95], v[232:235], v[104:107], v[80:95]
	s_waitcnt lgkmcnt(6)
	v_mfma_f32_32x32x16_bf16 v[80:95], v[236:239], v[108:111], v[80:95]
	s_waitcnt lgkmcnt(6)
	v_mfma_f32_32x32x16_bf16 v[96:111], v[224:227], v[112:115], v[48:63]
	ds_read_b64_tr_b16 v[128:129], v3 offset:0x400
	ds_read_b64_tr_b16 v[130:131], v3 offset:0xc00
	ds_read_b64_tr_b16 v[132:133], v3 offset:0x1400
	ds_read_b64_tr_b16 v[134:135], v3 offset:0x1c00
	ds_read_b64_tr_b16 v[136:137], v3 offset:0x2400
	ds_read_b64_tr_b16 v[138:139], v3 offset:0x2c00
	ds_read_b64_tr_b16 v[140:141], v3 offset:0x3400
	s_waitcnt lgkmcnt(6)
	v_mfma_f32_32x32x16_bf16 v[96:111], v[228:231], v[116:119], v[96:111]
	ds_read_b64_tr_b16 v[142:143], v3 offset:0x3c00
	s_waitcnt lgkmcnt(6)
	v_mfma_f32_32x32x16_bf16 v[96:111], v[232:235], v[120:123], v[96:111]
	s_waitcnt lgkmcnt(6)
	v_mfma_f32_32x32x16_bf16 v[96:111], v[236:239], v[124:127], v[96:111]
	s_waitcnt lgkmcnt(6)
	v_mfma_f32_32x32x16_bf16 v[112:127], v[224:227], v[128:131], v[64:79]
	ds_read_b64_tr_b16 v[240:241], v3 offset:0x600
	ds_read_b64_tr_b16 v[242:243], v3 offset:0xe00
	ds_read_b64_tr_b16 v[244:245], v3 offset:0x1600
	ds_read_b64_tr_b16 v[246:247], v3 offset:0x1e00
	ds_read_b64_tr_b16 v[248:249], v3 offset:0x2600
	ds_read_b64_tr_b16 v[250:251], v3 offset:0x2e00
	ds_read_b64_tr_b16 v[6:7], v3 offset:0x3600
	s_waitcnt lgkmcnt(6)
	v_mfma_f32_32x32x16_bf16 v[112:127], v[228:231], v[132:135], v[112:127]
	ds_read_b64_tr_b16 v[8:9], v3 offset:0x3e00
	s_waitcnt lgkmcnt(6)
	v_mfma_f32_32x32x16_bf16 v[112:127], v[232:235], v[136:139], v[112:127]
	s_waitcnt lgkmcnt(6)
	v_mfma_f32_32x32x16_bf16 v[112:127], v[236:239], v[140:143], v[112:127]
	s_waitcnt lgkmcnt(6)
	v_mfma_f32_32x32x16_bf16 v[128:143], v[224:227], v[240:243], v[32:47]
	s_mov_b64 s[0:1], 0
	s_waitcnt lgkmcnt(4)
	v_mfma_f32_32x32x16_bf16 v[128:143], v[228:231], v[244:247], v[128:143]
	s_waitcnt lgkmcnt(2)
	v_mfma_f32_32x32x16_bf16 v[128:143], v[232:235], v[248:251], v[128:143]
	s_waitcnt lgkmcnt(0)
	v_mfma_f32_32x32x16_bf16 v[128:143], v[236:239], v[6:9], v[128:143]
.LBB0_1218:
	s_andn2_b64 vcc, exec, s[0:1]
	s_cbranch_vccnz .LBB0_1226
	s_ashr_i32 s0, s53, 8
	s_lshl_b32 s0, s0, 2
	s_add_i32 s0, s0, 0
	v_add_u32_e32 v1, s0, v195
	v_add_u32_e32 v1, 0x18800, v1
	ds_read_b128 v[96:99], v1
	ds_read_b128 v[100:103], v1 offset:32
	ds_read_b128 v[80:83], v1 offset:128
	ds_read_b128 v[84:87], v1 offset:160
	ds_read_b128 v[104:107], v1 offset:64
	ds_read_b128 v[108:111], v1 offset:96
	ds_read_b128 v[88:91], v1 offset:192
	ds_read_b128 v[92:95], v1 offset:224
	s_add_i32 s0, s53, 0
	v_add3_u32 v1, s0, v197, v196
	v_add3_u32 v6, s0, v198, v196
	v_add3_u32 v7, s0, v199, v196
	v_add3_u32 v8, s0, v200, v196
	s_setprio 1
	ds_read_b128 v[112:115], v1 offset:49152
	ds_read_b128 v[116:119], v1 offset:49280
	s_waitcnt lgkmcnt(1)
	v_mfma_f32_32x32x16_bf16 v[96:111], v[112:115], v[172:175], v[96:111]
	ds_read_b128 v[112:115], v1 offset:57344
	ds_read_b128 v[120:123], v1 offset:57472
	s_waitcnt lgkmcnt(1)
	v_mfma_f32_32x32x16_bf16 v[80:95], v[112:115], v[172:175], v[80:95]
	ds_read_b128 v[112:115], v6 offset:49152
	ds_read_b128 v[124:127], v6 offset:49280
	s_waitcnt lgkmcnt(1)
	v_mfma_f32_32x32x16_bf16 v[96:111], v[112:115], v[168:171], v[96:111]
	ds_read_b128 v[112:115], v6 offset:57344
	ds_read_b128 v[128:131], v6 offset:57472
	s_waitcnt lgkmcnt(1)
	v_mfma_f32_32x32x16_bf16 v[80:95], v[112:115], v[168:171], v[80:95]
	ds_read_b128 v[112:115], v7 offset:49152
	ds_read_b128 v[132:135], v7 offset:49280
	s_waitcnt lgkmcnt(1)
	v_mfma_f32_32x32x16_bf16 v[96:111], v[112:115], v[164:167], v[96:111]
	ds_read_b128 v[112:115], v7 offset:57344
	ds_read_b128 v[136:139], v7 offset:57472
	s_waitcnt lgkmcnt(1)
	v_mfma_f32_32x32x16_bf16 v[80:95], v[112:115], v[164:167], v[80:95]
	ds_read_b128 v[112:115], v8 offset:49152
	ds_read_b128 v[140:143], v8 offset:49280
	s_waitcnt lgkmcnt(1)
	v_mfma_f32_32x32x16_bf16 v[96:111], v[112:115], v[160:163], v[96:111]
	ds_read_b128 v[112:115], v8 offset:57344
	ds_read_b128 v[164:167], v8 offset:57472
	s_waitcnt lgkmcnt(1)
	v_mfma_f32_32x32x16_bf16 v[80:95], v[112:115], v[160:163], v[80:95]
	v_mfma_f32_32x32x16_bf16 v[96:111], v[116:119], v[156:159], v[96:111]
	v_mfma_f32_32x32x16_bf16 v[80:95], v[120:123], v[156:159], v[80:95]
	v_mfma_f32_32x32x16_bf16 v[96:111], v[124:127], v[152:155], v[96:111]
	v_mfma_f32_32x32x16_bf16 v[80:95], v[128:131], v[152:155], v[80:95]
	v_mfma_f32_32x32x16_bf16 v[96:111], v[132:135], v[148:151], v[96:111]
	v_mfma_f32_32x32x16_bf16 v[80:95], v[136:139], v[148:151], v[80:95]
	v_mfma_f32_32x32x16_bf16 v[96:111], v[140:143], v[144:147], v[96:111]
	s_waitcnt lgkmcnt(0)
	v_mfma_f32_32x32x16_bf16 v[80:95], v[164:167], v[144:147], v[80:95]
	s_setprio 0
	v_add_f32_e32 v1, v213, v2
	v_add_f32_e32 v1, v216, v1
	v_add_f32_e32 v1, v211, v1
	v_add_f32_e32 v1, v214, v1
	v_add_f32_e32 v1, v210, v1
	v_add_f32_e32 v1, v212, v1
	v_add_f32_e32 v1, v205, v1
	v_add_f32_e32 v1, v208, v1
	v_add_f32_e32 v1, v203, v1
	v_add_f32_e32 v1, v206, v1
	v_add_f32_e32 v1, v202, v1
	v_add_f32_e32 v1, v209, v1
	v_add_f32_e32 v1, v204, v1
	v_add_f32_e32 v1, v207, v1
	v_add_f32_e32 v1, v13, v1
	v_add_f32_e32 v1, v14, v1
	v_add_f32_e32 v1, v15, v1
	v_add_f32_e32 v1, v218, v1
	v_add_f32_e32 v1, v219, v1
	v_add_f32_e32 v1, v220, v1
	v_add_f32_e32 v1, v221, v1
	v_add_f32_e32 v1, v222, v1
	v_add_f32_e32 v1, v4, v1
	v_add_f32_e32 v1, v223, v1
	v_add_f32_e32 v1, v252, v1
	v_add_f32_e32 v1, v253, v1
	v_add_f32_e32 v1, v254, v1
	v_add_f32_e32 v1, v10, v1
	v_add_f32_e32 v1, v11, v1
	v_add_f32_e32 v1, v12, v1
	v_mov_b32_e32 v2, v1
	s_nop 1
	v_permlane32_swap_b32_e32 v1, v2
	v_cvt_pk_bf16_f32 v112, v215, v217
	v_cvt_pk_bf16_f32 v113, v213, v216
	v_cvt_pk_bf16_f32 v114, v211, v214
	v_cvt_pk_bf16_f32 v115, v210, v212
	v_cvt_pk_bf16_f32 v116, v205, v208
	v_cvt_pk_bf16_f32 v117, v203, v206
	v_cvt_pk_bf16_f32 v118, v202, v209
	v_cvt_pk_bf16_f32 v119, v204, v207
	v_cvt_pk_bf16_f32 v120, v13, v14
	v_cvt_pk_bf16_f32 v121, v15, v218
	v_cvt_pk_bf16_f32 v122, v219, v220
	v_cvt_pk_bf16_f32 v123, v221, v222
	v_cvt_pk_bf16_f32 v6, v4, v223
	v_cvt_pk_bf16_f32 v7, v252, v253
	v_cvt_pk_bf16_f32 v8, v254, v10
	v_cvt_pk_bf16_f32 v9, v11, v12
	s_nop 0
	ds_read_b64_tr_b16 v[10:11], v3 offset:0
	ds_read_b64_tr_b16 v[12:13], v3 offset:0x800
	ds_read_b64_tr_b16 v[124:125], v3 offset:0x1000
	ds_read_b64_tr_b16 v[126:127], v3 offset:0x1800
	ds_read_b64_tr_b16 v[128:129], v3 offset:0x2000
	ds_read_b64_tr_b16 v[130:131], v3 offset:0x2800
	ds_read_b64_tr_b16 v[132:133], v3 offset:0x3000
	ds_read_b64_tr_b16 v[134:135], v3 offset:0x3800
	s_waitcnt lgkmcnt(6)
	s_nop 0
	v_mfma_f32_32x32x16_bf16 v[16:31], v[112:115], v[10:13], v[16:31]
	ds_read_b64_tr_b16 v[10:11], v3 offset:0x200
	ds_read_b64_tr_b16 v[12:13], v3 offset:0xa00
	s_waitcnt lgkmcnt(6)
	v_mfma_f32_32x32x16_bf16 v[16:31], v[116:119], v[124:127], v[16:31]
	ds_read_b64_tr_b16 v[124:125], v3 offset:0x1200
	ds_read_b64_tr_b16 v[126:127], v3 offset:0x1a00
	s_waitcnt lgkmcnt(6)
	v_mfma_f32_32x32x16_bf16 v[16:31], v[120:123], v[128:131], v[16:31]
	ds_read_b64_tr_b16 v[128:129], v3 offset:0x2200
	ds_read_b64_tr_b16 v[130:131], v3 offset:0x2a00
	ds_read_b64_tr_b16 v[136:137], v3 offset:0x3200
	ds_read_b64_tr_b16 v[138:139], v3 offset:0x3a00
	s_waitcnt lgkmcnt(6)
	v_mfma_f32_32x32x16_bf16 v[16:31], v[6:9], v[132:135], v[16:31]
	s_waitcnt lgkmcnt(6)
	v_mfma_f32_32x32x16_bf16 v[48:63], v[112:115], v[10:13], v[48:63]
	ds_read_b64_tr_b16 v[10:11], v3 offset:0x400
	ds_read_b64_tr_b16 v[12:13], v3 offset:0xc00
	s_waitcnt lgkmcnt(6)
	v_mfma_f32_32x32x16_bf16 v[48:63], v[116:119], v[124:127], v[48:63]
	ds_read_b64_tr_b16 v[124:125], v3 offset:0x1400
	ds_read_b64_tr_b16 v[126:127], v3 offset:0x1c00
	s_waitcnt lgkmcnt(6)
	v_mfma_f32_32x32x16_bf16 v[48:63], v[120:123], v[128:131], v[48:63]
	ds_read_b64_tr_b16 v[128:129], v3 offset:0x2400
	ds_read_b64_tr_b16 v[130:131], v3 offset:0x2c00
	ds_read_b64_tr_b16 v[132:133], v3 offset:0x3400
	ds_read_b64_tr_b16 v[134:135], v3 offset:0x3c00
	s_waitcnt lgkmcnt(6)
	v_mfma_f32_32x32x16_bf16 v[48:63], v[6:9], v[136:139], v[48:63]
	s_waitcnt lgkmcnt(6)
	v_mfma_f32_32x32x16_bf16 v[64:79], v[112:115], v[10:13], v[64:79]
	ds_read_b64_tr_b16 v[10:11], v3 offset:0x600
	ds_read_b64_tr_b16 v[12:13], v3 offset:0xe00
	s_waitcnt lgkmcnt(6)
	v_mfma_f32_32x32x16_bf16 v[64:79], v[116:119], v[124:127], v[64:79]
	ds_read_b64_tr_b16 v[124:125], v3 offset:0x1600
	ds_read_b64_tr_b16 v[126:127], v3 offset:0x1e00
	s_waitcnt lgkmcnt(6)
	v_mfma_f32_32x32x16_bf16 v[64:79], v[120:123], v[128:131], v[64:79]
	ds_read_b64_tr_b16 v[128:129], v3 offset:0x2600
	ds_read_b64_tr_b16 v[130:131], v3 offset:0x2e00
	ds_read_b64_tr_b16 v[136:137], v3 offset:0x3600
	ds_read_b64_tr_b16 v[138:139], v3 offset:0x3e00
	s_waitcnt lgkmcnt(6)
	v_mfma_f32_32x32x16_bf16 v[64:79], v[6:9], v[132:135], v[64:79]
	s_waitcnt lgkmcnt(6)
	v_mfma_f32_32x32x16_bf16 v[32:47], v[112:115], v[10:13], v[32:47]
	s_sub_i32 s0, s52, s67
	s_lshl_b32 s0, s0, 6
	s_or_b32 s1, s0, 63
	s_cmp_le_i32 s1, s69
	s_waitcnt lgkmcnt(4)
	v_mfma_f32_32x32x16_bf16 v[32:47], v[116:119], v[124:127], v[32:47]
	s_waitcnt lgkmcnt(2)
	v_mfma_f32_32x32x16_bf16 v[32:47], v[120:123], v[128:131], v[32:47]
	s_waitcnt lgkmcnt(0)
	v_mfma_f32_32x32x16_bf16 v[32:47], v[6:9], v[136:139], v[32:47]
	s_cbranch_scc1 .LBB0_1221
	v_subrev_u32_e32 v3, s0, v192
	v_cmp_gt_u32_e32 vcc, 2.0, v3
	v_add_u32_e32 v4, 0xbfffffe0, v3
	s_nop 0
	v_cndmask_b32_e32 v96, v179, v96, vcc
	v_cmp_lt_u32_e32 vcc, s96, v4
	v_add_u32_e32 v4, 0xbfffffff, v3
	s_nop 0
	v_cndmask_b32_e32 v80, v179, v80, vcc
	v_cmp_lt_u32_e32 vcc, s96, v4
	v_add_u32_e32 v4, 0xbfffffdf, v3
	s_nop 0
	v_cndmask_b32_e32 v97, v179, v97, vcc
	v_cmp_lt_u32_e32 vcc, s96, v4
	v_add_u32_e32 v4, 0xbffffffe, v3
	s_nop 0
	v_cndmask_b32_e32 v81, v179, v81, vcc
	v_cmp_lt_u32_e32 vcc, s96, v4
	v_add_u32_e32 v4, 0xbfffffde, v3
	s_nop 0
	v_cndmask_b32_e32 v98, v179, v98, vcc
	v_cmp_lt_u32_e32 vcc, s96, v4
	v_add_u32_e32 v4, 0xbffffffd, v3
	s_nop 0
	v_cndmask_b32_e32 v82, v179, v82, vcc
	v_cmp_lt_u32_e32 vcc, s96, v4
	v_add_u32_e32 v4, 0xbfffffdd, v3
	s_nop 0
	v_cndmask_b32_e32 v99, v179, v99, vcc
	v_cmp_lt_u32_e32 vcc, s96, v4
	v_add_u32_e32 v4, 0xbffffff8, v3
	s_nop 0
	v_cndmask_b32_e32 v83, v179, v83, vcc
	v_cmp_lt_u32_e32 vcc, s96, v4
	v_add_u32_e32 v4, 0xbfffffd8, v3
	s_nop 0
	v_cndmask_b32_e32 v100, v179, v100, vcc
	v_cmp_lt_u32_e32 vcc, s96, v4
	v_add_u32_e32 v4, 0xbffffff7, v3
	s_nop 0
	v_cndmask_b32_e32 v84, v179, v84, vcc
	v_cmp_lt_u32_e32 vcc, s96, v4
	v_add_u32_e32 v4, 0xbfffffd7, v3
	s_nop 0
	v_cndmask_b32_e32 v101, v179, v101, vcc
	v_cmp_lt_u32_e32 vcc, s96, v4
	v_add_u32_e32 v4, 0xbffffff6, v3
	s_nop 0
	v_cndmask_b32_e32 v85, v179, v85, vcc
	v_cmp_lt_u32_e32 vcc, s96, v4
	v_add_u32_e32 v4, 0xbfffffd6, v3
	s_nop 0
	v_cndmask_b32_e32 v102, v179, v102, vcc
	v_cmp_lt_u32_e32 vcc, s96, v4
	v_add_u32_e32 v4, 0xbffffff5, v3
	s_nop 0
	v_cndmask_b32_e32 v86, v179, v86, vcc
	v_cmp_lt_u32_e32 vcc, s96, v4
	v_add_u32_e32 v4, 0xbfffffd5, v3
	s_nop 0
	v_cndmask_b32_e32 v103, v179, v103, vcc
	v_cmp_lt_u32_e32 vcc, s96, v4
	v_add_u32_e32 v4, 0xbffffff0, v3
	s_nop 0
	v_cndmask_b32_e32 v87, v179, v87, vcc
	v_cmp_lt_u32_e32 vcc, s96, v4
	v_add_u32_e32 v4, 0xbfffffd0, v3
	s_nop 0
	v_cndmask_b32_e32 v104, v179, v104, vcc
	v_cmp_lt_u32_e32 vcc, s96, v4
	v_add_u32_e32 v4, 0xbfffffef, v3
	s_nop 0
	v_cndmask_b32_e32 v88, v179, v88, vcc
	v_cmp_lt_u32_e32 vcc, s96, v4
	v_add_u32_e32 v4, 0xbfffffcf, v3
	s_nop 0
	v_cndmask_b32_e32 v105, v179, v105, vcc
	v_cmp_lt_u32_e32 vcc, s96, v4
	v_add_u32_e32 v4, 0xbfffffee, v3
	s_nop 0
	v_cndmask_b32_e32 v89, v179, v89, vcc
	v_cmp_lt_u32_e32 vcc, s96, v4
	v_add_u32_e32 v4, 0xbfffffce, v3
	s_nop 0
	v_cndmask_b32_e32 v106, v179, v106, vcc
	v_cmp_lt_u32_e32 vcc, s96, v4
	v_add_u32_e32 v4, 0xbfffffed, v3
	s_nop 0
	v_cndmask_b32_e32 v90, v179, v90, vcc
	v_cmp_lt_u32_e32 vcc, s96, v4
	v_add_u32_e32 v4, 0xbfffffcd, v3
	s_nop 0
	v_cndmask_b32_e32 v107, v179, v107, vcc
	v_cmp_lt_u32_e32 vcc, s96, v4
	v_add_u32_e32 v4, 0xbfffffe8, v3
	s_nop 0
	v_cndmask_b32_e32 v91, v179, v91, vcc
	v_cmp_lt_u32_e32 vcc, s96, v4
	v_add_u32_e32 v4, 0xbfffffc8, v3
	s_nop 0
	v_cndmask_b32_e32 v108, v179, v108, vcc
	v_cmp_lt_u32_e32 vcc, s96, v4
	v_add_u32_e32 v4, 0xbfffffe7, v3
	s_nop 0
	v_cndmask_b32_e32 v92, v179, v92, vcc
	v_cmp_lt_u32_e32 vcc, s96, v4
	v_add_u32_e32 v4, 0xbfffffc7, v3
	s_nop 0
	v_cndmask_b32_e32 v109, v179, v109, vcc
	v_cmp_lt_u32_e32 vcc, s96, v4
	v_add_u32_e32 v4, 0xbfffffe6, v3
	s_nop 0
	v_cndmask_b32_e32 v93, v179, v93, vcc
	v_cmp_lt_u32_e32 vcc, s96, v4
	v_add_u32_e32 v4, 0xbfffffc6, v3
	s_nop 0
	v_cndmask_b32_e32 v110, v179, v110, vcc
	v_cmp_lt_u32_e32 vcc, s96, v4
	v_add_u32_e32 v4, 0xbfffffe5, v3
	v_add_u32_e32 v3, 0xbfffffc5, v3
	v_cndmask_b32_e32 v94, v179, v94, vcc
	v_cmp_lt_u32_e32 vcc, s96, v4
	s_nop 1
	v_cndmask_b32_e32 v111, v179, v111, vcc
	v_cmp_lt_u32_e32 vcc, s96, v3
	s_nop 1
	v_cndmask_b32_e32 v95, v179, v95, vcc

.LBB0_1225:
	v_cndmask_b32_e64 v4, v4, v201, s[6:7]
	v_mul_f32_e32 v4, 0xbe0293ee, v4
	v_fmamk_f32 v6, v96, 0x3e0293ee, v4
	v_fmamk_f32 v7, v97, 0x3e0293ee, v4
	v_exp_f32_e32 v6, v6
	v_fmamk_f32 v8, v98, 0x3e0293ee, v4
	v_exp_f32_e32 v7, v7
	v_fmamk_f32 v9, v99, 0x3e0293ee, v4
	v_exp_f32_e32 v8, v8
	v_fmamk_f32 v10, v100, 0x3e0293ee, v4
	v_exp_f32_e32 v9, v9
	v_fmamk_f32 v11, v101, 0x3e0293ee, v4
	v_exp_f32_e32 v10, v10
	v_add_f32_e32 v2, v1, v2
	v_add_f32_e32 v1, 0, v6
	v_fmamk_f32 v12, v102, 0x3e0293ee, v4
	v_exp_f32_e32 v11, v11
	v_add_f32_e32 v1, v7, v1
	v_fmamk_f32 v13, v103, 0x3e0293ee, v4
	v_exp_f32_e32 v12, v12
	v_add_f32_e32 v1, v8, v1
	v_fmamk_f32 v14, v104, 0x3e0293ee, v4
	v_exp_f32_e32 v13, v13
	v_add_f32_e32 v1, v9, v1
	v_fmamk_f32 v15, v105, 0x3e0293ee, v4
	v_exp_f32_e32 v14, v14
	v_add_f32_e32 v1, v10, v1
	v_fmamk_f32 v96, v106, 0x3e0293ee, v4
	v_exp_f32_e32 v15, v15
	v_add_f32_e32 v1, v11, v1
	v_fmamk_f32 v97, v107, 0x3e0293ee, v4
	v_fmamk_f32 v98, v108, 0x3e0293ee, v4
	v_fmamk_f32 v99, v109, 0x3e0293ee, v4
	v_fmamk_f32 v100, v110, 0x3e0293ee, v4
	v_fmamk_f32 v101, v111, 0x3e0293ee, v4
	v_fmamk_f32 v80, v80, 0x3e0293ee, v4
	v_fmamk_f32 v81, v81, 0x3e0293ee, v4
	v_fmamk_f32 v82, v82, 0x3e0293ee, v4
	v_fmamk_f32 v83, v83, 0x3e0293ee, v4
	v_fmamk_f32 v84, v84, 0x3e0293ee, v4
	v_fmamk_f32 v85, v85, 0x3e0293ee, v4
	v_fmamk_f32 v86, v86, 0x3e0293ee, v4
	v_fmamk_f32 v87, v87, 0x3e0293ee, v4
	v_fmamk_f32 v88, v88, 0x3e0293ee, v4
	v_fmamk_f32 v89, v89, 0x3e0293ee, v4
	v_fmamk_f32 v90, v90, 0x3e0293ee, v4
	v_fmamk_f32 v91, v91, 0x3e0293ee, v4
	v_fmamk_f32 v92, v92, 0x3e0293ee, v4
	v_fmamk_f32 v93, v93, 0x3e0293ee, v4
	v_fmamk_f32 v94, v94, 0x3e0293ee, v4
	v_fmac_f32_e32 v4, 0x3e0293ee, v95
	v_exp_f32_e32 v95, v96
	v_add_f32_e32 v1, v12, v1
	v_exp_f32_e32 v96, v97
	v_add_f32_e32 v1, v13, v1
	v_exp_f32_e32 v97, v98
	v_add_f32_e32 v1, v14, v1
	v_exp_f32_e32 v98, v99
	v_add_f32_e32 v1, v15, v1
	v_exp_f32_e32 v99, v100
	v_add_f32_e32 v1, v95, v1
	v_exp_f32_e32 v100, v101
	v_add_f32_e32 v1, v96, v1
	v_exp_f32_e32 v80, v80
	v_add_f32_e32 v1, v97, v1
	v_exp_f32_e32 v81, v81
	v_add_f32_e32 v1, v98, v1
	v_exp_f32_e32 v82, v82
	v_add_f32_e32 v1, v99, v1
	v_exp_f32_e32 v83, v83
	v_add_f32_e32 v1, v100, v1
	v_exp_f32_e32 v84, v84
	v_add_f32_e32 v1, v80, v1
	v_exp_f32_e32 v85, v85
	v_add_f32_e32 v1, v81, v1
	v_exp_f32_e32 v86, v86
	v_add_f32_e32 v1, v82, v1
	v_exp_f32_e32 v87, v87
	v_add_f32_e32 v1, v83, v1
	v_exp_f32_e32 v88, v88
	v_add_f32_e32 v1, v84, v1
	v_exp_f32_e32 v89, v89
	v_add_f32_e32 v1, v85, v1
	v_exp_f32_e32 v90, v90
	v_add_f32_e32 v1, v86, v1
	v_exp_f32_e32 v91, v91
	v_add_f32_e32 v1, v87, v1
	v_exp_f32_e32 v92, v92
	v_add_f32_e32 v1, v88, v1
	v_exp_f32_e32 v93, v93
	v_add_f32_e32 v1, v89, v1
	v_exp_f32_e32 v94, v94
	v_add_f32_e32 v1, v90, v1
	v_exp_f32_e32 v101, v4
	v_add_f32_e32 v1, v91, v1
	v_add_f32_e32 v1, v92, v1
	v_add_f32_e32 v1, v93, v1
	v_add_f32_e32 v1, v94, v1
	v_add_f32_e32 v1, v101, v1
	v_mov_b32_e32 v4, v1
	s_nop 1
	v_permlane32_swap_b32_e32 v1, v4
	v_fmac_f32_e32 v2, v194, v5
	s_waitcnt vmcnt(0) lgkmcnt(0)
	s_barrier
	v_add_f32_e32 v1, v1, v4
	v_fmac_f32_e32 v1, v2, v3
	v_cvt_pk_bf16_f32 v2, v6, v7
	v_cvt_pk_bf16_f32 v3, v8, v9
	v_cvt_pk_bf16_f32 v4, v10, v11
	v_cvt_pk_bf16_f32 v5, v12, v13
	v_cvt_pk_bf16_f32 v6, v14, v15
	v_cvt_pk_bf16_f32 v7, v95, v96
	v_cvt_pk_bf16_f32 v8, v97, v98
	v_cvt_pk_bf16_f32 v9, v99, v100
	v_cvt_pk_bf16_f32 v10, v80, v81
	v_cvt_pk_bf16_f32 v11, v82, v83
	v_cvt_pk_bf16_f32 v12, v84, v85
	v_cvt_pk_bf16_f32 v13, v86, v87
	v_cvt_pk_bf16_f32 v80, v88, v89
	v_cvt_pk_bf16_f32 v81, v90, v91
	v_cvt_pk_bf16_f32 v82, v92, v93
	v_cvt_pk_bf16_f32 v83, v94, v101
	s_nop 0
	v_add_u32_e32 v14, s53, v193
	ds_read_b64_tr_b16 v[84:85], v14 offset:0
	ds_read_b64_tr_b16 v[86:87], v14 offset:0x800
	ds_read_b64_tr_b16 v[88:89], v14 offset:0x1000
	ds_read_b64_tr_b16 v[90:91], v14 offset:0x1800
	ds_read_b64_tr_b16 v[92:93], v14 offset:0x2000
	ds_read_b64_tr_b16 v[94:95], v14 offset:0x2800
	ds_read_b64_tr_b16 v[96:97], v14 offset:0x3000
	ds_read_b64_tr_b16 v[98:99], v14 offset:0x3800
	s_waitcnt lgkmcnt(6)
	s_nop 0
	v_mfma_f32_32x32x16_bf16 v[16:31], v[2:5], v[84:87], v[16:31]
	ds_read_b64_tr_b16 v[84:85], v14 offset:0x200
	ds_read_b64_tr_b16 v[86:87], v14 offset:0xa00
	s_waitcnt lgkmcnt(6)
	v_mfma_f32_32x32x16_bf16 v[16:31], v[6:9], v[88:91], v[16:31]
	ds_read_b64_tr_b16 v[88:89], v14 offset:0x1200
	ds_read_b64_tr_b16 v[90:91], v14 offset:0x1a00
	s_waitcnt lgkmcnt(6)
	v_mfma_f32_32x32x16_bf16 v[16:31], v[10:13], v[92:95], v[16:31]
	ds_read_b64_tr_b16 v[92:93], v14 offset:0x2200
	ds_read_b64_tr_b16 v[94:95], v14 offset:0x2a00
	ds_read_b64_tr_b16 v[100:101], v14 offset:0x3200
	ds_read_b64_tr_b16 v[102:103], v14 offset:0x3a00
	s_waitcnt lgkmcnt(6)
	v_mfma_f32_32x32x16_bf16 v[16:31], v[80:83], v[96:99], v[16:31]
	s_waitcnt lgkmcnt(6)
	v_mfma_f32_32x32x16_bf16 v[48:63], v[2:5], v[84:87], v[48:63]
	ds_read_b64_tr_b16 v[84:85], v14 offset:0x400
	ds_read_b64_tr_b16 v[86:87], v14 offset:0xc00
	s_waitcnt lgkmcnt(6)
	v_mfma_f32_32x32x16_bf16 v[48:63], v[6:9], v[88:91], v[48:63]
	ds_read_b64_tr_b16 v[88:89], v14 offset:0x1400
	ds_read_b64_tr_b16 v[90:91], v14 offset:0x1c00
	s_waitcnt lgkmcnt(6)
	v_mfma_f32_32x32x16_bf16 v[48:63], v[10:13], v[92:95], v[48:63]
	ds_read_b64_tr_b16 v[92:93], v14 offset:0x2400
	ds_read_b64_tr_b16 v[94:95], v14 offset:0x2c00
	ds_read_b64_tr_b16 v[96:97], v14 offset:0x3400
	ds_read_b64_tr_b16 v[98:99], v14 offset:0x3c00
	s_waitcnt lgkmcnt(6)
	v_mfma_f32_32x32x16_bf16 v[48:63], v[80:83], v[100:103], v[48:63]
	s_waitcnt lgkmcnt(6)
	v_mfma_f32_32x32x16_bf16 v[64:79], v[2:5], v[84:87], v[64:79]
	ds_read_b64_tr_b16 v[84:85], v14 offset:0x600
	ds_read_b64_tr_b16 v[86:87], v14 offset:0xe00
	s_waitcnt lgkmcnt(6)
	v_mfma_f32_32x32x16_bf16 v[64:79], v[6:9], v[88:91], v[64:79]
	ds_read_b64_tr_b16 v[88:89], v14 offset:0x1600
	ds_read_b64_tr_b16 v[90:91], v14 offset:0x1e00
	s_waitcnt lgkmcnt(6)
	v_mfma_f32_32x32x16_bf16 v[64:79], v[10:13], v[92:95], v[64:79]
	ds_read_b64_tr_b16 v[92:93], v14 offset:0x2600
	ds_read_b64_tr_b16 v[94:95], v14 offset:0x2e00
	ds_read_b64_tr_b16 v[100:101], v14 offset:0x3600
	ds_read_b64_tr_b16 v[102:103], v14 offset:0x3e00
	s_waitcnt lgkmcnt(6)
	v_mfma_f32_32x32x16_bf16 v[64:79], v[80:83], v[96:99], v[64:79]
	s_waitcnt lgkmcnt(6)
	v_mfma_f32_32x32x16_bf16 v[32:47], v[2:5], v[84:87], v[32:47]
	s_nop 10
	v_mov_b64_e32 v[126:127], v[78:79]
	s_mov_b32 s68, s53
	s_mov_b32 s65, s66
	s_mov_b32 s53, s8
	v_mov_b64_e32 v[124:125], v[76:77]
	v_mov_b64_e32 v[122:123], v[74:75]
	v_mov_b64_e32 v[120:121], v[72:73]
	s_waitcnt lgkmcnt(4)
	v_mfma_f32_32x32x16_bf16 v[32:47], v[6:9], v[88:91], v[32:47]
	v_mov_b64_e32 v[118:119], v[70:71]
	v_mov_b64_e32 v[116:117], v[68:69]
	v_mov_b64_e32 v[114:115], v[66:67]
	v_mov_b64_e32 v[112:113], v[64:65]
	s_waitcnt lgkmcnt(2)
	v_mfma_f32_32x32x16_bf16 v[32:47], v[10:13], v[92:95], v[32:47]
	s_waitcnt lgkmcnt(0)
	v_mfma_f32_32x32x16_bf16 v[32:47], v[80:83], v[100:103], v[32:47]
	v_mov_b64_e32 v[110:111], v[62:63]
	v_mov_b64_e32 v[94:95], v[30:31]
	v_mov_b64_e32 v[108:109], v[60:61]
	v_mov_b64_e32 v[106:107], v[58:59]
	v_mov_b64_e32 v[104:105], v[56:57]
	v_mov_b64_e32 v[102:103], v[54:55]
	v_mov_b64_e32 v[100:101], v[52:53]
	s_nop 4
	v_mov_b64_e32 v[142:143], v[46:47]
	v_mov_b64_e32 v[98:99], v[50:51]
	v_mov_b64_e32 v[96:97], v[48:49]
	v_mov_b64_e32 v[140:141], v[44:45]
	v_mov_b64_e32 v[138:139], v[42:43]
	v_mov_b64_e32 v[136:137], v[40:41]
	v_mov_b64_e32 v[134:135], v[38:39]
	v_mov_b64_e32 v[132:133], v[36:37]
	v_mov_b64_e32 v[130:131], v[34:35]
	v_mov_b64_e32 v[128:129], v[32:33]
	v_mov_b64_e32 v[92:93], v[28:29]
	v_mov_b64_e32 v[90:91], v[26:27]
	v_mov_b64_e32 v[88:89], v[24:25]
	v_mov_b64_e32 v[86:87], v[22:23]
	v_mov_b64_e32 v[84:85], v[20:21]
	v_mov_b64_e32 v[82:83], v[18:19]
	v_mov_b64_e32 v[80:81], v[16:17]
	s_branch .LBB0_1227
